# speedup vs baseline: 1.0815x; 1.0106x over previous
; DEV f32x4 mfma16(bf16x8 a, bf16x8 b, f32x4 c) { return __builtin_amdgcn_mfma_f32_16x16x32_bf16(a, b, c, 0, 0, 0); }
; DEV void gemm_tile(const u16* __restrict__ A, size_t lda, const u16* __restrict__ Bt, size_t ldb, int K,
;                    u16* sA, u16* sB, f32x4 (&acc)[8][4]) {
;     ...
;   for (int kt = 0; kt < nk; ++kt) {
;     const int st = kt & 1;
;     if (kt + 1 < nk) S_STORE(st ^ 1)
;     if (kt + 2 < nk) G_LOAD((kt + 2) << 5)
;     {
;       const u16* pa = sAr + st * 12288;
;       const u16* pb = sBr + st * 12288;
;       bf16x8 b[4];
; #pragma unroll
;       for (int ni = 0; ni < 4; ++ni) b[ni] = *(const bf16x8*)(pb + ni * 16 * 32);
; #pragma unroll
;       for (int mh = 0; mh < 2; ++mh) {
;         bf16x8 a[4];
; #pragma unroll
;         for (int mi = 0; mi < 4; ++mi) a[mi] = *(const bf16x8*)(pa + (mh * 64 + mi * 16) * 32);
; #pragma unroll
;         for (int mi = 0; mi < 4; ++mi)
; #pragma unroll
;           for (int ni = 0; ni < 4; ++ni) acc[mh * 4 + mi][ni] = mfma16(a[mi], b[ni], acc[mh * 4 + mi][ni]);
;       }
;     }
;     __syncthreads();
;   }
.LBB0_198:
	v_add_u32_e32 v229, s8, v166
	v_add_u32_e32 v228, s8, v156
	ds_read_b128 v[116:119], v229 offset:16384
	ds_read_b128 v[168:171], v228
	ds_read_b128 v[128:131], v229 offset:17408
	ds_read_b128 v[140:143], v229 offset:18432
	ds_read_b128 v[120:123], v229 offset:19456
	ds_read_b128 v[152:155], v228 offset:1024
	ds_read_b128 v[172:175], v228 offset:2048
	ds_read_b128 v[132:135], v228 offset:3072
	s_waitcnt lgkmcnt(6)
	v_mfma_f32_16x16x32_bf16 v[148:151], v[168:171], v[116:119], v[148:151]
	s_waitcnt lgkmcnt(5)
	v_mfma_f32_16x16x32_bf16 v[144:147], v[168:171], v[128:131], v[144:147]
	s_waitcnt lgkmcnt(4)
	v_mfma_f32_16x16x32_bf16 v[124:127], v[168:171], v[140:143], v[124:127]
	s_waitcnt lgkmcnt(3)
	v_mfma_f32_16x16x32_bf16 v[112:115], v[168:171], v[120:123], v[112:115]
	ds_read_b128 v[232:235], v228 offset:4096
	ds_read_b128 v[236:239], v228 offset:5120
	s_waitcnt lgkmcnt(4)
	v_mfma_f32_16x16x32_bf16 v[108:111], v[152:155], v[116:119], v[108:111]
	s_add_i32 m0, s9, 0x0
	v_mfma_f32_16x16x32_bf16 v[104:107], v[152:155], v[128:131], v[104:107]
	global_load_lds_dwordx4 v[136:137], off
	v_lshl_add_u64 v[136:137], v[136:137], 0, 64
	global_load_dwordx4 v[244:247], v[136:137], off
	v_lshl_add_u64 v[136:137], v[136:137], 0, 64
	v_mfma_f32_16x16x32_bf16 v[100:103], v[152:155], v[140:143], v[100:103]
	s_add_i32 m0, s9, 0x1000
	v_mfma_f32_16x16x32_bf16 v[96:99], v[152:155], v[120:123], v[96:99]
	global_load_lds_dwordx4 v[138:139], off
	v_lshl_add_u64 v[138:139], v[138:139], 0, 64
	global_load_dwordx4 v[252:255], v[138:139], off
	v_lshl_add_u64 v[138:139], v[138:139], 0, 64
	s_waitcnt lgkmcnt(3)
	v_mfma_f32_16x16x32_bf16 v[92:95], v[172:175], v[116:119], v[92:95]
	s_add_i32 m0, s9, 0x2000
	v_mfma_f32_16x16x32_bf16 v[88:91], v[172:175], v[128:131], v[88:91]
	global_load_lds_dwordx4 v[176:177], off
	v_lshl_add_u64 v[176:177], v[176:177], 0, 64
	global_load_dwordx4 v[208:211], v[176:177], off
	v_lshl_add_u64 v[176:177], v[176:177], 0, 64
	v_mfma_f32_16x16x32_bf16 v[84:87], v[172:175], v[140:143], v[84:87]
	s_add_i32 m0, s9, 0x3000
	v_mfma_f32_16x16x32_bf16 v[80:83], v[172:175], v[120:123], v[80:83]
	ds_read_b128 v[240:243], v228 offset:6144
	ds_read_b128 v[168:171], v228 offset:7168
	s_waitcnt lgkmcnt(4)
	v_mfma_f32_16x16x32_bf16 v[76:79], v[132:135], v[116:119], v[76:79]
	global_load_lds_dwordx4 v[186:187], off
	v_lshl_add_u64 v[186:187], v[186:187], 0, 64
	global_load_dwordx4 v[212:215], v[186:187], off
	v_lshl_add_u64 v[186:187], v[186:187], 0, 64
	v_mfma_f32_16x16x32_bf16 v[72:75], v[132:135], v[128:131], v[72:75]
	s_add_i32 m0, s9, 0x4000
	v_mfma_f32_16x16x32_bf16 v[68:71], v[132:135], v[140:143], v[68:71]
	global_load_lds_dwordx4 v[188:189], off
	v_lshl_add_u64 v[188:189], v[188:189], 0, 64
	global_load_dwordx4 v[216:219], v[188:189], off
	v_lshl_add_u64 v[188:189], v[188:189], 0, 64
	v_mfma_f32_16x16x32_bf16 v[64:67], v[132:135], v[120:123], v[64:67]
	s_add_i32 m0, s9, 0x5000
	s_waitcnt lgkmcnt(3)
	v_mfma_f32_16x16x32_bf16 v[60:63], v[232:235], v[116:119], v[60:63]
	global_load_lds_dwordx4 v[192:193], off
	v_lshl_add_u64 v[192:193], v[192:193], 0, 64
	global_load_dwordx4 v[220:223], v[192:193], off
	v_lshl_add_u64 v[192:193], v[192:193], 0, 64
	v_mfma_f32_16x16x32_bf16 v[56:59], v[232:235], v[128:131], v[56:59]
	s_add_i32 s9, s8, s5
	s_add_i32 s8, s8, 0x6000
	v_mfma_f32_16x16x32_bf16 v[52:55], v[232:235], v[140:143], v[52:55]
	s_cmp_eq_u32 s8, 0x12000
	s_cselect_b32 s8, 0, s8
	v_mfma_f32_16x16x32_bf16 v[48:51], v[232:235], v[120:123], v[48:51]
	s_add_u32 s6, s6, 64
	s_addc_u32 s7, s7, 0
	s_cmpk_lg_i32 s6, 0xf80
	s_waitcnt lgkmcnt(2)
	v_mfma_f32_16x16x32_bf16 v[44:47], v[236:239], v[116:119], v[44:47]
	v_mfma_f32_16x16x32_bf16 v[40:43], v[236:239], v[128:131], v[40:43]
	v_mfma_f32_16x16x32_bf16 v[36:39], v[236:239], v[140:143], v[36:39]
	v_mfma_f32_16x16x32_bf16 v[32:35], v[236:239], v[120:123], v[32:35]
	s_waitcnt lgkmcnt(1)
	v_mfma_f32_16x16x32_bf16 v[28:31], v[240:243], v[116:119], v[28:31]
	v_mfma_f32_16x16x32_bf16 v[24:27], v[240:243], v[128:131], v[24:27]
	v_mfma_f32_16x16x32_bf16 v[20:23], v[240:243], v[140:143], v[20:23]
	v_mfma_f32_16x16x32_bf16 v[16:19], v[240:243], v[120:123], v[16:19]
	s_waitcnt lgkmcnt(0)
	s_waitcnt vmcnt(12)
	s_barrier
	v_mfma_f32_16x16x32_bf16 v[12:15], v[168:171], v[116:119], v[12:15]
	v_mfma_f32_16x16x32_bf16 v[8:11], v[168:171], v[128:131], v[8:11]
	v_mfma_f32_16x16x32_bf16 v[4:7], v[168:171], v[140:143], v[4:7]
	v_mfma_f32_16x16x32_bf16 v[0:3], v[168:171], v[120:123], v[0:3]
	v_add_u32_e32 v229, s8, v166
	v_add_u32_e32 v228, s8, v156
	ds_read_b128 v[116:119], v229 offset:16384
	ds_read_b128 v[168:171], v228
	ds_read_b128 v[128:131], v229 offset:17408
	ds_read_b128 v[140:143], v229 offset:18432
	ds_read_b128 v[120:123], v229 offset:19456
	ds_read_b128 v[152:155], v228 offset:1024
	ds_read_b128 v[172:175], v228 offset:2048
	ds_read_b128 v[132:135], v228 offset:3072
	s_waitcnt lgkmcnt(6)
	v_mfma_f32_16x16x32_bf16 v[148:151], v[168:171], v[116:119], v[148:151]
	s_waitcnt lgkmcnt(5)
	v_mfma_f32_16x16x32_bf16 v[144:147], v[168:171], v[128:131], v[144:147]
	s_waitcnt lgkmcnt(4)
	v_mfma_f32_16x16x32_bf16 v[124:127], v[168:171], v[140:143], v[124:127]
	s_waitcnt lgkmcnt(3)
	v_mfma_f32_16x16x32_bf16 v[112:115], v[168:171], v[120:123], v[112:115]
	ds_read_b128 v[232:235], v228 offset:4096
	ds_read_b128 v[236:239], v228 offset:5120
	s_waitcnt lgkmcnt(4)
	v_mfma_f32_16x16x32_bf16 v[108:111], v[152:155], v[116:119], v[108:111]
	v_mfma_f32_16x16x32_bf16 v[104:107], v[152:155], v[128:131], v[104:107]
	v_mfma_f32_16x16x32_bf16 v[100:103], v[152:155], v[140:143], v[100:103]
	v_mfma_f32_16x16x32_bf16 v[96:99], v[152:155], v[120:123], v[96:99]
	s_waitcnt lgkmcnt(3)
; DEV f32x4 mfma16(bf16x8 a, bf16x8 b, f32x4 c) { return __builtin_amdgcn_mfma_f32_16x16x32_bf16(a, b, c, 0, 0, 0); }
; DEV void gemm_tile(const u16* __restrict__ A, size_t lda, const u16* __restrict__ Bt, size_t ldb, int K,
;                    u16* sA, u16* sB, f32x4 (&acc)[8][4]) {
;     ...
;   for (int kt = 0; kt < nk; ++kt) {
;     const int st = kt & 1;
;     if (kt + 1 < nk) S_STORE(st ^ 1)
;     if (kt + 2 < nk) G_LOAD((kt + 2) << 5)
;     {
;       const u16* pa = sAr + st * 12288;
;       const u16* pb = sBr + st * 12288;
;       bf16x8 b[4];
; #pragma unroll
;       for (int ni = 0; ni < 4; ++ni) b[ni] = *(const bf16x8*)(pb + ni * 16 * 32);
; #pragma unroll
;       for (int mh = 0; mh < 2; ++mh) {
;         bf16x8 a[4];
; #pragma unroll
;         for (int mi = 0; mi < 4; ++mi) a[mi] = *(const bf16x8*)(pa + (mh * 64 + mi * 16) * 32);
; #pragma unroll
;         for (int mi = 0; mi < 4; ++mi)
; #pragma unroll
;           for (int ni = 0; ni < 4; ++ni) acc[mh * 4 + mi][ni] = mfma16(a[mi], b[ni], acc[mh * 4 + mi][ni]);
;       }
;     }
;     __syncthreads();
;   }
	v_mfma_f32_16x16x32_bf16 v[92:95], v[172:175], v[116:119], v[92:95]
	v_mfma_f32_16x16x32_bf16 v[88:91], v[172:175], v[128:131], v[88:91]
	v_mfma_f32_16x16x32_bf16 v[84:87], v[172:175], v[140:143], v[84:87]
	v_mfma_f32_16x16x32_bf16 v[80:83], v[172:175], v[120:123], v[80:83]
	ds_read_b128 v[240:243], v228 offset:6144
	ds_read_b128 v[168:171], v228 offset:7168
	s_waitcnt lgkmcnt(4)
	v_mfma_f32_16x16x32_bf16 v[76:79], v[132:135], v[116:119], v[76:79]
	s_waitcnt vmcnt(0)
	v_add_u32_e32 v231, s9, v230
	v_mfma_f32_16x16x32_bf16 v[72:75], v[132:135], v[128:131], v[72:75]
	ds_write_b128 v231, v[244:247]
	v_mfma_f32_16x16x32_bf16 v[68:71], v[132:135], v[140:143], v[68:71]
	ds_write_b128 v231, v[252:255] offset:4096
	v_mfma_f32_16x16x32_bf16 v[64:67], v[132:135], v[120:123], v[64:67]
	ds_write_b128 v231, v[208:211] offset:8192
	s_waitcnt lgkmcnt(6)
	v_mfma_f32_16x16x32_bf16 v[60:63], v[232:235], v[116:119], v[60:63]
	ds_write_b128 v231, v[212:215] offset:12288
	v_mfma_f32_16x16x32_bf16 v[56:59], v[232:235], v[128:131], v[56:59]
	ds_write_b128 v231, v[216:219] offset:16384
	v_mfma_f32_16x16x32_bf16 v[52:55], v[232:235], v[140:143], v[52:55]
	ds_write_b128 v231, v[220:223] offset:20480
	v_mfma_f32_16x16x32_bf16 v[48:51], v[232:235], v[120:123], v[48:51]
	s_add_i32 s9, s8, s5
	s_add_i32 s8, s8, 0x6000
	s_waitcnt lgkmcnt(8)
	v_mfma_f32_16x16x32_bf16 v[44:47], v[236:239], v[116:119], v[44:47]
	s_cmp_eq_u32 s8, 0x12000
	s_cselect_b32 s8, 0, s8
	v_mfma_f32_16x16x32_bf16 v[40:43], v[236:239], v[128:131], v[40:43]
	s_add_u32 s6, s6, 64
	s_addc_u32 s7, s7, 0
	s_cmpk_lg_i32 s6, 0xf80
	v_mfma_f32_16x16x32_bf16 v[36:39], v[236:239], v[140:143], v[36:39]
	v_mfma_f32_16x16x32_bf16 v[32:35], v[236:239], v[120:123], v[32:35]
	s_waitcnt lgkmcnt(7)
	v_mfma_f32_16x16x32_bf16 v[28:31], v[240:243], v[116:119], v[28:31]
	v_mfma_f32_16x16x32_bf16 v[24:27], v[240:243], v[128:131], v[24:27]
	v_mfma_f32_16x16x32_bf16 v[20:23], v[240:243], v[140:143], v[20:23]
	v_mfma_f32_16x16x32_bf16 v[16:19], v[240:243], v[120:123], v[16:19]
	s_waitcnt lgkmcnt(6)
	s_waitcnt lgkmcnt(0)
	s_barrier
	v_mfma_f32_16x16x32_bf16 v[12:15], v[168:171], v[116:119], v[12:15]
	v_mfma_f32_16x16x32_bf16 v[8:11], v[168:171], v[128:131], v[8:11]
	v_mfma_f32_16x16x32_bf16 v[4:7], v[168:171], v[140:143], v[4:7]
	v_mfma_f32_16x16x32_bf16 v[0:3], v[168:171], v[120:123], v[0:3]
	s_cbranch_scc1 .LBB0_198
	ds_read_b128 v[116:119], v166 offset:16384
	ds_read_b128 v[120:123], v166 offset:17408
	ds_read_b128 v[128:131], v166 offset:18432
	ds_read_b128 v[132:135], v166 offset:19456
	ds_read_b128 v[136:139], v156
	ds_read_b128 v[140:143], v156 offset:1024
	ds_read_b128 v[152:155], v156 offset:2048
	ds_read_b128 v[162:165], v156 offset:3072
	s_movk_i32 s5, 0x2200
	s_waitcnt lgkmcnt(3)
	v_mfma_f32_16x16x32_bf16 v[148:151], v[136:139], v[116:119], v[148:151]
	s_movk_i32 s8, 0x110
	v_mfma_f32_16x16x32_bf16 v[144:147], v[136:139], v[120:123], v[144:147]
	v_mfma_f32_16x16x32_bf16 v[124:127], v[136:139], v[128:131], v[124:127]
	v_mfma_f32_16x16x32_bf16 v[112:115], v[136:139], v[132:135], v[112:115]
	s_waitcnt lgkmcnt(2)
	v_mfma_f32_16x16x32_bf16 v[108:111], v[140:143], v[116:119], v[108:111]
	v_mfma_f32_16x16x32_bf16 v[104:107], v[140:143], v[120:123], v[104:107]
	v_mfma_f32_16x16x32_bf16 v[100:103], v[140:143], v[128:131], v[100:103]
	v_mfma_f32_16x16x32_bf16 v[96:99], v[140:143], v[132:135], v[96:99]
	s_waitcnt lgkmcnt(1)
	v_mfma_f32_16x16x32_bf16 v[92:95], v[152:155], v[116:119], v[92:95]
	v_mfma_f32_16x16x32_bf16 v[88:91], v[152:155], v[120:123], v[88:91]
	v_mfma_f32_16x16x32_bf16 v[84:87], v[152:155], v[128:131], v[84:87]
	v_mfma_f32_16x16x32_bf16 v[80:83], v[152:155], v[132:135], v[80:83]
	s_waitcnt lgkmcnt(0)
	v_mfma_f32_16x16x32_bf16 v[76:79], v[162:165], v[116:119], v[76:79]
	v_mfma_f32_16x16x32_bf16 v[72:75], v[162:165], v[120:123], v[72:75]
	v_mfma_f32_16x16x32_bf16 v[68:71], v[162:165], v[128:131], v[68:71]
	v_mfma_f32_16x16x32_bf16 v[64:67], v[162:165], v[132:135], v[64:67]
	ds_read_b128 v[136:139], v156 offset:4096
	ds_read_b128 v[140:143], v156 offset:5120
	ds_read_b128 v[152:155], v156 offset:6144
	ds_read_b128 v[162:165], v156 offset:7168
	s_waitcnt lgkmcnt(0)
	s_waitcnt vmcnt(0)
	s_barrier
	v_mfma_f32_16x16x32_bf16 v[60:63], v[136:139], v[116:119], v[60:63]
	v_mfma_f32_16x16x32_bf16 v[56:59], v[136:139], v[120:123], v[56:59]
	v_mfma_f32_16x16x32_bf16 v[52:55], v[136:139], v[128:131], v[52:55]
	v_mfma_f32_16x16x32_bf16 v[48:51], v[136:139], v[132:135], v[48:51]
	v_mfma_f32_16x16x32_bf16 v[44:47], v[140:143], v[116:119], v[44:47]
	v_mfma_f32_16x16x32_bf16 v[40:43], v[140:143], v[120:123], v[40:43]
	v_mfma_f32_16x16x32_bf16 v[36:39], v[140:143], v[128:131], v[36:39]
	v_mfma_f32_16x16x32_bf16 v[32:35], v[140:143], v[132:135], v[32:35]
	v_mfma_f32_16x16x32_bf16 v[28:31], v[152:155], v[116:119], v[28:31]
	v_mfma_f32_16x16x32_bf16 v[24:27], v[152:155], v[120:123], v[24:27]
	v_mfma_f32_16x16x32_bf16 v[20:23], v[152:155], v[128:131], v[20:23]
	v_mfma_f32_16x16x32_bf16 v[16:19], v[152:155], v[132:135], v[16:19]
	v_mfma_f32_16x16x32_bf16 v[12:15], v[162:165], v[116:119], v[12:15]
	v_mfma_f32_16x16x32_bf16 v[8:11], v[162:165], v[120:123], v[8:11]
	v_mfma_f32_16x16x32_bf16 v[4:7], v[162:165], v[128:131], v[4:7]
	v_mfma_f32_16x16x32_bf16 v[0:3], v[162:165], v[132:135], v[0:3]
	ds_read_b128 v[116:119], v166 offset:40960
	ds_read_b128 v[120:123], v166 offset:41984
	ds_read_b128 v[128:131], v166 offset:43008
	ds_read_b128 v[132:135], v166 offset:44032
	ds_read_b128 v[136:139], v156 offset:24576
	ds_read_b128 v[140:143], v156 offset:25600
	ds_read_b128 v[152:155], v156 offset:26624
	ds_read_b128 v[162:165], v156 offset:27648
	s_waitcnt lgkmcnt(3)
; DEV f32x4 mfma16(bf16x8 a, bf16x8 b, f32x4 c) { return __builtin_amdgcn_mfma_f32_16x16x32_bf16(a, b, c, 0, 0, 0); }
; DEV void gemm_tile(const u16* __restrict__ A, size_t lda, const u16* __restrict__ Bt, size_t ldb, int K,
;                    u16* sA, u16* sB, f32x4 (&acc)[8][4]) {
;     ...
;         for (int mi = 0; mi < 4; ++mi) a[mi] = *(const bf16x8*)(pa + (mh * 64 + mi * 16) * 32);
; #pragma unroll
;         for (int mi = 0; mi < 4; ++mi)
; #pragma unroll
;           for (int ni = 0; ni < 4; ++ni) acc[mh * 4 + mi][ni] = mfma16(a[mi], b[ni], acc[mh * 4 + mi][ni]);
; DEV void store_tile_f32_add(const f32x4 (&acc)[8][4], const float* xres, float* out, int m0, int n0, unsigned char* smem) {
;     ...
;   const int chunk = lane & 15;
; #pragma unroll
;   for (int mq = 0; mq < 4; ++mq) {
; #pragma unroll
;     for (int mh = 0; mh < 2; ++mh)
; #pragma unroll
;       for (int ni = 0; ni < 4; ++ni)
; #pragma unroll
;         for (int j = 0; j < 4; ++j) st[(mh * 16 + fq * 4 + j) * 68 + ni * 16 + fr] = acc[mq * 2 + mh][ni][j];
; #pragma unroll
;     for (int itr = 0; itr < 8; ++itr) {
;       const int rl = (lane >> 4) + 4 * itr;
;       const f32x4 v = *(const f32x4*)(st + rl * 68 + chunk * 4);
;       const size_t idx = (size_t)(m0 + wr * 128 + mq * 32 + rl) * 2048 + n0 + wc * 64 + chunk * 4;
;       const f32x4 x = *(const f32x4*)(xres + idx);
;       *(f32x4*)(out + idx) = x + v;
;     }
	v_mfma_f32_16x16x32_bf16 v[148:151], v[136:139], v[116:119], v[148:151]
	v_mfma_f32_16x16x32_bf16 v[144:147], v[136:139], v[120:123], v[144:147]
	v_mfma_f32_16x16x32_bf16 v[124:127], v[136:139], v[128:131], v[124:127]
	v_mfma_f32_16x16x32_bf16 v[112:115], v[136:139], v[132:135], v[112:115]
	s_waitcnt lgkmcnt(2)
	v_mfma_f32_16x16x32_bf16 v[108:111], v[140:143], v[116:119], v[108:111]
	v_mfma_f32_16x16x32_bf16 v[104:107], v[140:143], v[120:123], v[104:107]
	v_mfma_f32_16x16x32_bf16 v[136:139], v[140:143], v[128:131], v[100:103]
	v_mfma_f32_16x16x32_bf16 v[96:99], v[140:143], v[132:135], v[96:99]
	s_waitcnt lgkmcnt(1)
	v_mfma_f32_16x16x32_bf16 v[92:95], v[152:155], v[116:119], v[92:95]
	v_mfma_f32_16x16x32_bf16 v[88:91], v[152:155], v[120:123], v[88:91]
	v_mfma_f32_16x16x32_bf16 v[84:87], v[152:155], v[128:131], v[84:87]
	v_mfma_f32_16x16x32_bf16 v[80:83], v[152:155], v[132:135], v[80:83]
	s_waitcnt lgkmcnt(0)
	v_mfma_f32_16x16x32_bf16 v[76:79], v[162:165], v[116:119], v[76:79]
	v_mfma_f32_16x16x32_bf16 v[72:75], v[162:165], v[120:123], v[72:75]
	v_mfma_f32_16x16x32_bf16 v[68:71], v[162:165], v[128:131], v[68:71]
	v_mfma_f32_16x16x32_bf16 v[64:67], v[162:165], v[132:135], v[64:67]
	ds_read_b128 v[100:103], v156 offset:28672
	ds_read_b128 v[140:143], v156 offset:29696
	ds_read_b128 v[152:155], v156 offset:30720
	ds_read_b128 v[162:165], v156 offset:31744
	s_waitcnt lgkmcnt(0)
	s_barrier
	v_mfma_f32_16x16x32_bf16 v[60:63], v[100:103], v[116:119], v[60:63]
	v_mfma_f32_16x16x32_bf16 v[56:59], v[100:103], v[120:123], v[56:59]
	v_mfma_f32_16x16x32_bf16 v[52:55], v[100:103], v[128:131], v[52:55]
	v_mfma_f32_16x16x32_bf16 v[48:51], v[100:103], v[132:135], v[48:51]
	v_mov_b32_e32 v102, v178
	s_nop 0
	v_lshrrev_b32_e32 v101, 6, v102
	v_and_b32_e32 v103, 15, v102
	v_mfma_f32_16x16x32_bf16 v[44:47], v[140:143], v[116:119], v[44:47]
	v_mul_lo_u32 v101, v101, s5
	v_bfe_u32 v100, v102, 4, 2
	v_mfma_f32_16x16x32_bf16 v[28:31], v[152:155], v[116:119], v[28:31]
	v_mfma_f32_16x16x32_bf16 v[12:15], v[162:165], v[116:119], v[12:15]
	v_lshlrev_b32_e32 v116, 2, v103
	v_or_b32_e32 v117, v101, v116
	v_and_b32_e32 v101, 0xffffff80, v102
	v_add_u32_e32 v101, s4, v101
	s_movk_i32 s4, 0x440
	v_mad_u32_u24 v118, v103, 12, v117
	v_and_or_b32 v116, v102, 64, v116
	v_mad_u32_u24 v103, v100, s4, v117
	v_readlane_b32 s4, v251, 7
	ds_write_b32 v103, v148
	ds_write_b32 v103, v149 offset:272
	ds_write_b32 v103, v150 offset:544
	ds_write_b32 v103, v151 offset:816
	ds_write_b32 v103, v144 offset:64
	ds_write_b32 v103, v145 offset:336
	ds_write_b32 v103, v146 offset:608
	ds_write_b32 v103, v147 offset:880
	ds_write_b32 v103, v124 offset:128
	ds_write_b32 v103, v125 offset:400
	ds_write_b32 v103, v126 offset:672
	ds_write_b32 v103, v127 offset:944
	ds_write_b32 v103, v112 offset:192
	ds_write_b32 v103, v113 offset:464
	ds_write_b32 v103, v114 offset:736
	ds_write_b32 v103, v115 offset:1008
	ds_write_b32 v103, v108 offset:4352
	ds_write_b32 v103, v109 offset:4624
	ds_write_b32 v103, v110 offset:4896
	ds_write_b32 v103, v111 offset:5168
	ds_write_b32 v103, v104 offset:4416
	ds_write_b32 v103, v105 offset:4688
	ds_write_b32 v103, v106 offset:4960
	ds_write_b32 v103, v107 offset:5232
	ds_write_b32 v103, v136 offset:4480
	ds_write_b32 v103, v137 offset:4752
	ds_write_b32 v103, v138 offset:5024
	ds_write_b32 v103, v139 offset:5296
	ds_write_b32 v103, v96 offset:4544
	ds_write_b32 v103, v97 offset:4816
	ds_write_b32 v103, v98 offset:5088
	ds_write_b32 v103, v99 offset:5360
	v_or_b32_e32 v98, v101, v100
	v_lshlrev_b32_e32 v156, 2, v116
	v_readlane_b32 s6, v251, 9
	v_readlane_b32 s7, v251, 10
	v_ashrrev_i32_e32 v99, 31, v98
	v_lshlrev_b64 v[98:99], 13, v[98:99]
	v_lshl_add_u64 v[96:97], s[6:7], 0, v[156:157]
	v_lshl_add_u64 v[96:97], s[2:3], 2, v[96:97]
	v_lshl_add_u64 v[98:99], v[96:97], 0, v[98:99]
	v_mov_b32_e32 v242, 0x8000
	v_mov_b32_e32 v243, 0
	v_mov_b64_e32 v[240:241], v[98:99]
	global_load_dwordx4 v[108:111], v[98:99], off
	v_lshl_add_u64 v[240:241], v[240:241], 0, v[242:243]
	global_load_dwordx4 v[208:211], v[240:241], off
	v_lshl_add_u64 v[240:241], v[240:241], 0, v[242:243]
	global_load_dwordx4 v[212:215], v[240:241], off
	v_lshl_add_u64 v[240:241], v[240:241], 0, v[242:243]
	global_load_dwordx4 v[216:219], v[240:241], off
	v_lshl_add_u64 v[240:241], v[240:241], 0, v[242:243]
	global_load_dwordx4 v[220:223], v[240:241], off
	v_lshl_add_u64 v[240:241], v[240:241], 0, v[242:243]
	global_load_dwordx4 v[224:227], v[240:241], off
	v_lshl_add_u64 v[240:241], v[240:241], 0, v[242:243]
	global_load_dwordx4 v[232:235], v[240:241], off
	v_lshl_add_u64 v[240:241], v[240:241], 0, v[242:243]
	global_load_dwordx4 v[236:239], v[240:241], off
	v_mad_u32_u24 v102, v100, s8, v118
	ds_read_b128 v[104:107], v102
	v_mfma_f32_16x16x32_bf16 v[32:35], v[140:143], v[132:135], v[32:35]
	v_readlane_b32 s5, v251, 8
	s_waitcnt vmcnt(7) lgkmcnt(0)
	v_pk_add_f32 v[106:107], v[106:107], v[110:111]
	v_pk_add_f32 v[104:105], v[104:105], v[108:109]
	global_store_dwordx4 v[98:99], v[104:107], off
	v_or_b32_e32 v99, 4, v100
	v_or_b32_e32 v108, v99, v101
	v_ashrrev_i32_e32 v109, 31, v108
	v_lshlrev_b64 v[108:109], 13, v[108:109]
	v_lshl_add_u64 v[112:113], v[96:97], 0, v[108:109]
	v_mad_u32_u24 v98, v99, s8, v118
	ds_read_b128 v[104:107], v98
	v_mfma_f32_16x16x32_bf16 v[40:43], v[140:143], v[120:123], v[40:43]
	s_waitcnt vmcnt(7) lgkmcnt(0)
; DEV void store_tile_f32_add(const f32x4 (&acc)[8][4], const float* xres, float* out, int m0, int n0, unsigned char* smem) {
;     ...
; #pragma unroll
;   for (int mq = 0; mq < 4; ++mq) {
; #pragma unroll
;     for (int mh = 0; mh < 2; ++mh)
; #pragma unroll
;       for (int ni = 0; ni < 4; ++ni)
; #pragma unroll
;         for (int j = 0; j < 4; ++j) st[(mh * 16 + fq * 4 + j) * 68 + ni * 16 + fr] = acc[mq * 2 + mh][ni][j];
; #pragma unroll
;     for (int itr = 0; itr < 8; ++itr) {
;       const int rl = (lane >> 4) + 4 * itr;
;       const f32x4 v = *(const f32x4*)(st + rl * 68 + chunk * 4);
;       const size_t idx = (size_t)(m0 + wr * 128 + mq * 32 + rl) * 2048 + n0 + wc * 64 + chunk * 4;
;       const f32x4 x = *(const f32x4*)(xres + idx);
;       *(f32x4*)(out + idx) = x + v;
;     }
	v_mov_b64_e32 v[108:109], v[208:209]
	v_mov_b64_e32 v[110:111], v[210:211]
	v_pk_add_f32 v[106:107], v[106:107], v[110:111]
	v_pk_add_f32 v[104:105], v[104:105], v[108:109]
	global_store_dwordx4 v[112:113], v[104:107], off
	ds_read_b128 v[106:109], v98 offset:1088
	v_mfma_f32_16x16x32_bf16 v[36:39], v[140:143], v[128:131], v[36:39]
	v_or_b32_e32 v104, 8, v100
	v_or_b32_e32 v110, v104, v101
	v_ashrrev_i32_e32 v111, 31, v110
	v_lshlrev_b64 v[110:111], 13, v[110:111]
	v_lshl_add_u64 v[114:115], v[96:97], 0, v[110:111]
	v_or_b32_e32 v105, 12, v100
	v_mfma_f32_16x16x32_bf16 v[8:11], v[162:165], v[120:123], v[8:11]
	s_waitcnt vmcnt(7) lgkmcnt(0)
	v_mov_b64_e32 v[110:111], v[212:213]
	v_mov_b64_e32 v[112:113], v[214:215]
	v_pk_add_f32 v[106:107], v[106:107], v[110:111]
	v_or_b32_e32 v110, v105, v101
	v_ashrrev_i32_e32 v111, 31, v110
	v_pk_add_f32 v[108:109], v[108:109], v[112:113]
	v_lshlrev_b64 v[110:111], 13, v[110:111]
	global_store_dwordx4 v[114:115], v[106:109], off
	v_lshl_add_u64 v[114:115], v[96:97], 0, v[110:111]
	ds_read_b128 v[106:109], v98 offset:2176
	v_mfma_f32_16x16x32_bf16 v[24:27], v[152:155], v[120:123], v[24:27]
	s_waitcnt vmcnt(7) lgkmcnt(0)
	v_mov_b64_e32 v[110:111], v[216:217]
	v_mov_b64_e32 v[112:113], v[218:219]
	v_pk_add_f32 v[108:109], v[108:109], v[112:113]
	v_pk_add_f32 v[106:107], v[106:107], v[110:111]
	global_store_dwordx4 v[114:115], v[106:109], off
	ds_read_b128 v[108:111], v98 offset:3264
	v_mfma_f32_16x16x32_bf16 v[20:23], v[152:155], v[128:131], v[20:23]
	v_or_b32_e32 v106, 16, v100
	v_or_b32_e32 v112, v106, v101
	v_ashrrev_i32_e32 v113, 31, v112
	v_lshlrev_b64 v[112:113], 13, v[112:113]
	v_lshl_add_u64 v[116:117], v[96:97], 0, v[112:113]
	v_or_b32_e32 v107, 20, v100
	v_mfma_f32_16x16x32_bf16 v[16:19], v[152:155], v[132:135], v[16:19]
	s_waitcnt vmcnt(7) lgkmcnt(0)
	v_mov_b64_e32 v[112:113], v[220:221]
	v_mov_b64_e32 v[114:115], v[222:223]
	v_pk_add_f32 v[108:109], v[108:109], v[112:113]
	v_or_b32_e32 v112, v107, v101
	v_ashrrev_i32_e32 v113, 31, v112
	v_pk_add_f32 v[110:111], v[110:111], v[114:115]
	v_lshlrev_b64 v[112:113], 13, v[112:113]
	global_store_dwordx4 v[116:117], v[108:111], off
	v_lshl_add_u64 v[116:117], v[96:97], 0, v[112:113]
	ds_read_b128 v[108:111], v98 offset:4352
	v_mfma_f32_16x16x32_bf16 v[4:7], v[162:165], v[128:131], v[4:7]
	s_waitcnt vmcnt(7) lgkmcnt(0)
	v_mov_b64_e32 v[112:113], v[224:225]
	v_mov_b64_e32 v[114:115], v[226:227]
	v_pk_add_f32 v[110:111], v[110:111], v[114:115]
	v_pk_add_f32 v[108:109], v[108:109], v[112:113]
	global_store_dwordx4 v[116:117], v[108:111], off
	ds_read_b128 v[110:113], v98 offset:5440
	v_mfma_f32_16x16x32_bf16 v[0:3], v[162:165], v[132:135], v[0:3]
	v_or_b32_e32 v108, 24, v100
	v_or_b32_e32 v114, v108, v101
	v_ashrrev_i32_e32 v115, 31, v114
	v_lshlrev_b64 v[114:115], 13, v[114:115]
	v_lshl_add_u64 v[118:119], v[96:97], 0, v[114:115]
	v_or_b32_e32 v109, 28, v100
	s_waitcnt vmcnt(7) lgkmcnt(0)
	v_mov_b64_e32 v[114:115], v[232:233]
	v_mov_b64_e32 v[116:117], v[234:235]
	v_pk_add_f32 v[110:111], v[110:111], v[114:115]
	v_or_b32_e32 v114, v109, v101
	v_ashrrev_i32_e32 v115, 31, v114
	v_pk_add_f32 v[112:113], v[112:113], v[116:117]
	v_lshlrev_b64 v[114:115], 13, v[114:115]
	global_store_dwordx4 v[118:119], v[110:113], off
	v_lshl_add_u64 v[118:119], v[96:97], 0, v[114:115]
	ds_read_b128 v[110:113], v98 offset:6528
	s_waitcnt vmcnt(7) lgkmcnt(0)
	v_mov_b64_e32 v[114:115], v[236:237]
	v_mov_b64_e32 v[116:117], v[238:239]
	v_pk_add_f32 v[112:113], v[112:113], v[116:117]
	v_pk_add_f32 v[110:111], v[110:111], v[114:115]
	global_store_dwordx4 v[118:119], v[110:113], off
	ds_write_b32 v103, v92
	ds_write_b32 v103, v93 offset:272
	ds_write_b32 v103, v94 offset:544
	ds_write_b32 v103, v95 offset:816
	ds_write_b32 v103, v88 offset:64
	ds_write_b32 v103, v89 offset:336
	ds_write_b32 v103, v90 offset:608
	ds_write_b32 v103, v91 offset:880
	ds_write_b32 v103, v84 offset:128
	ds_write_b32 v103, v85 offset:400
	ds_write_b32 v103, v86 offset:672
	ds_write_b32 v103, v87 offset:944
	ds_write_b32 v103, v80 offset:192
	ds_write_b32 v103, v81 offset:464
	ds_write_b32 v103, v82 offset:736
	ds_write_b32 v103, v83 offset:1008
	ds_write_b32 v103, v76 offset:4352
	ds_write_b32 v103, v77 offset:4624
	ds_write_b32 v103, v78 offset:4896
	ds_write_b32 v103, v79 offset:5168
	ds_write_b32 v103, v72 offset:4416
	ds_write_b32 v103, v73 offset:4688
	ds_write_b32 v103, v74 offset:4960
	ds_write_b32 v103, v75 offset:5232
	ds_write_b32 v103, v68 offset:4480
	ds_write_b32 v103, v69 offset:4752
	ds_write_b32 v103, v70 offset:5024
	ds_write_b32 v103, v71 offset:5296
	ds_write_b32 v103, v64 offset:4544
	ds_write_b32 v103, v65 offset:4816
	ds_write_b32 v103, v66 offset:5088
	ds_write_b32 v103, v67 offset:5360
	v_or_b32_e32 v64, 32, v101
	v_or_b32_e32 v70, v64, v100
	v_ashrrev_i32_e32 v71, 31, v70
	v_lshlrev_b64 v[70:71], 13, v[70:71]
	v_lshl_add_u64 v[74:75], v[96:97], 0, v[70:71]
	v_mov_b32_e32 v242, 0x8000
	v_mov_b32_e32 v243, 0
	v_mov_b64_e32 v[240:241], v[74:75]
	global_load_dwordx4 v[70:73], v[74:75], off
	v_lshl_add_u64 v[240:241], v[240:241], 0, v[242:243]
	global_load_dwordx4 v[208:211], v[240:241], off
	v_lshl_add_u64 v[240:241], v[240:241], 0, v[242:243]
	global_load_dwordx4 v[212:215], v[240:241], off
	v_lshl_add_u64 v[240:241], v[240:241], 0, v[242:243]
	global_load_dwordx4 v[216:219], v[240:241], off
	v_lshl_add_u64 v[240:241], v[240:241], 0, v[242:243]
	global_load_dwordx4 v[220:223], v[240:241], off
	v_lshl_add_u64 v[240:241], v[240:241], 0, v[242:243]
	global_load_dwordx4 v[224:227], v[240:241], off
	v_lshl_add_u64 v[240:241], v[240:241], 0, v[242:243]
	global_load_dwordx4 v[232:235], v[240:241], off
	v_lshl_add_u64 v[240:241], v[240:241], 0, v[242:243]
	global_load_dwordx4 v[236:239], v[240:241], off
	ds_read_b128 v[66:69], v102
	s_waitcnt vmcnt(7) lgkmcnt(0)
; DEV void store_tile_f32_add(const f32x4 (&acc)[8][4], const float* xres, float* out, int m0, int n0, unsigned char* smem) {
;     ...
; #pragma unroll
;   for (int mq = 0; mq < 4; ++mq) {
; #pragma unroll
;     for (int mh = 0; mh < 2; ++mh)
; #pragma unroll
;       for (int ni = 0; ni < 4; ++ni)
; #pragma unroll
;         for (int j = 0; j < 4; ++j) st[(mh * 16 + fq * 4 + j) * 68 + ni * 16 + fr] = acc[mq * 2 + mh][ni][j];
; #pragma unroll
;     for (int itr = 0; itr < 8; ++itr) {
;       const int rl = (lane >> 4) + 4 * itr;
;       const f32x4 v = *(const f32x4*)(st + rl * 68 + chunk * 4);
;       const size_t idx = (size_t)(m0 + wr * 128 + mq * 32 + rl) * 2048 + n0 + wc * 64 + chunk * 4;
;       const f32x4 x = *(const f32x4*)(xres + idx);
;       *(f32x4*)(out + idx) = x + v;
;     }
	v_pk_add_f32 v[66:67], v[66:67], v[70:71]
	v_or_b32_e32 v70, v64, v99
	v_ashrrev_i32_e32 v71, 31, v70
	v_pk_add_f32 v[68:69], v[68:69], v[72:73]
	v_lshlrev_b64 v[70:71], 13, v[70:71]
	global_store_dwordx4 v[74:75], v[66:69], off
	v_lshl_add_u64 v[74:75], v[96:97], 0, v[70:71]
	ds_read_b128 v[66:69], v98
	s_waitcnt vmcnt(7) lgkmcnt(0)
	v_mov_b64_e32 v[70:71], v[208:209]
	v_mov_b64_e32 v[72:73], v[210:211]
	v_pk_add_f32 v[66:67], v[66:67], v[70:71]
	v_or_b32_e32 v70, v64, v104
	v_ashrrev_i32_e32 v71, 31, v70
	v_pk_add_f32 v[68:69], v[68:69], v[72:73]
	v_lshlrev_b64 v[70:71], 13, v[70:71]
	global_store_dwordx4 v[74:75], v[66:69], off
	v_lshl_add_u64 v[74:75], v[96:97], 0, v[70:71]
	ds_read_b128 v[66:69], v98 offset:1088
	s_waitcnt vmcnt(7) lgkmcnt(0)
	v_mov_b64_e32 v[70:71], v[212:213]
	v_mov_b64_e32 v[72:73], v[214:215]
	v_pk_add_f32 v[66:67], v[66:67], v[70:71]
	v_or_b32_e32 v70, v64, v105
	v_ashrrev_i32_e32 v71, 31, v70
	v_pk_add_f32 v[68:69], v[68:69], v[72:73]
	v_lshlrev_b64 v[70:71], 13, v[70:71]
	global_store_dwordx4 v[74:75], v[66:69], off
	v_lshl_add_u64 v[74:75], v[96:97], 0, v[70:71]
	ds_read_b128 v[66:69], v98 offset:2176
	s_waitcnt vmcnt(7) lgkmcnt(0)
	v_mov_b64_e32 v[70:71], v[216:217]
	v_mov_b64_e32 v[72:73], v[218:219]
	v_pk_add_f32 v[66:67], v[66:67], v[70:71]
	v_or_b32_e32 v70, v64, v106
	v_ashrrev_i32_e32 v71, 31, v70
	v_pk_add_f32 v[68:69], v[68:69], v[72:73]
	v_lshlrev_b64 v[70:71], 13, v[70:71]
	global_store_dwordx4 v[74:75], v[66:69], off
	v_lshl_add_u64 v[74:75], v[96:97], 0, v[70:71]
	ds_read_b128 v[66:69], v98 offset:3264
	s_waitcnt vmcnt(7) lgkmcnt(0)
	v_mov_b64_e32 v[70:71], v[220:221]
	v_mov_b64_e32 v[72:73], v[222:223]
	v_pk_add_f32 v[66:67], v[66:67], v[70:71]
	v_or_b32_e32 v70, v64, v107
	v_ashrrev_i32_e32 v71, 31, v70
	v_pk_add_f32 v[68:69], v[68:69], v[72:73]
	v_lshlrev_b64 v[70:71], 13, v[70:71]
	global_store_dwordx4 v[74:75], v[66:69], off
	v_lshl_add_u64 v[74:75], v[96:97], 0, v[70:71]
	ds_read_b128 v[66:69], v98 offset:4352
	s_waitcnt vmcnt(7) lgkmcnt(0)
	v_mov_b64_e32 v[70:71], v[224:225]
	v_mov_b64_e32 v[72:73], v[226:227]
	v_pk_add_f32 v[66:67], v[66:67], v[70:71]
	v_or_b32_e32 v70, v64, v108
	v_ashrrev_i32_e32 v71, 31, v70
	v_pk_add_f32 v[68:69], v[68:69], v[72:73]
	v_lshlrev_b64 v[70:71], 13, v[70:71]
	global_store_dwordx4 v[74:75], v[66:69], off
	v_lshl_add_u64 v[74:75], v[96:97], 0, v[70:71]
	ds_read_b128 v[66:69], v98 offset:5440
	v_or_b32_e32 v64, v64, v109
	v_ashrrev_i32_e32 v65, 31, v64
	v_lshlrev_b64 v[64:65], 13, v[64:65]
	v_lshl_add_u64 v[64:65], v[96:97], 0, v[64:65]
	s_waitcnt vmcnt(7) lgkmcnt(0)
	v_mov_b64_e32 v[70:71], v[232:233]
	v_mov_b64_e32 v[72:73], v[234:235]
	v_pk_add_f32 v[68:69], v[68:69], v[72:73]
	v_pk_add_f32 v[66:67], v[66:67], v[70:71]
	s_nop 0
	global_store_dwordx4 v[74:75], v[66:69], off
	ds_read_b128 v[66:69], v98 offset:6528
	s_waitcnt vmcnt(7) lgkmcnt(0)
	v_mov_b64_e32 v[70:71], v[236:237]
	v_mov_b64_e32 v[72:73], v[238:239]
	v_pk_add_f32 v[68:69], v[68:69], v[72:73]
	v_pk_add_f32 v[66:67], v[66:67], v[70:71]
	global_store_dwordx4 v[64:65], v[66:69], off
	ds_write_b32 v103, v60
	ds_write_b32 v103, v61 offset:272
	ds_write_b32 v103, v62 offset:544
	ds_write_b32 v103, v63 offset:816
	ds_write_b32 v103, v56 offset:64
	ds_write_b32 v103, v57 offset:336
	ds_write_b32 v103, v58 offset:608
	ds_write_b32 v103, v59 offset:880
	ds_write_b32 v103, v52 offset:128
	ds_write_b32 v103, v53 offset:400
	ds_write_b32 v103, v54 offset:672
	ds_write_b32 v103, v55 offset:944
	ds_write_b32 v103, v48 offset:192
	ds_write_b32 v103, v49 offset:464
	ds_write_b32 v103, v50 offset:736
	ds_write_b32 v103, v51 offset:1008
	ds_write_b32 v103, v44 offset:4352
	ds_write_b32 v103, v45 offset:4624
	ds_write_b32 v103, v46 offset:4896
	ds_write_b32 v103, v47 offset:5168
	ds_write_b32 v103, v40 offset:4416
	ds_write_b32 v103, v41 offset:4688
	ds_write_b32 v103, v42 offset:4960
	ds_write_b32 v103, v43 offset:5232
	ds_write_b32 v103, v36 offset:4480
	ds_write_b32 v103, v37 offset:4752
	ds_write_b32 v103, v38 offset:5024
	ds_write_b32 v103, v39 offset:5296
	ds_write_b32 v103, v32 offset:4544
	ds_write_b32 v103, v33 offset:4816
	ds_write_b32 v103, v34 offset:5088
	ds_write_b32 v103, v35 offset:5360
	v_or_b32_e32 v32, 64, v101
	v_or_b32_e32 v38, v32, v100
	v_ashrrev_i32_e32 v39, 31, v38
	v_lshlrev_b64 v[38:39], 13, v[38:39]
	v_lshl_add_u64 v[42:43], v[96:97], 0, v[38:39]
	v_mov_b32_e32 v242, 0x8000
	v_mov_b32_e32 v243, 0
	v_mov_b64_e32 v[240:241], v[42:43]
	global_load_dwordx4 v[38:41], v[42:43], off
	v_lshl_add_u64 v[240:241], v[240:241], 0, v[242:243]
	global_load_dwordx4 v[208:211], v[240:241], off
	v_lshl_add_u64 v[240:241], v[240:241], 0, v[242:243]
	global_load_dwordx4 v[212:215], v[240:241], off
	v_lshl_add_u64 v[240:241], v[240:241], 0, v[242:243]
	global_load_dwordx4 v[216:219], v[240:241], off
	v_lshl_add_u64 v[240:241], v[240:241], 0, v[242:243]
	global_load_dwordx4 v[220:223], v[240:241], off
	v_lshl_add_u64 v[240:241], v[240:241], 0, v[242:243]
	global_load_dwordx4 v[224:227], v[240:241], off
	v_lshl_add_u64 v[240:241], v[240:241], 0, v[242:243]
	global_load_dwordx4 v[232:235], v[240:241], off
	v_lshl_add_u64 v[240:241], v[240:241], 0, v[242:243]
	global_load_dwordx4 v[236:239], v[240:241], off
	ds_read_b128 v[34:37], v102
	s_waitcnt vmcnt(7) lgkmcnt(0)
	v_pk_add_f32 v[34:35], v[34:35], v[38:39]
	v_or_b32_e32 v38, v32, v99
	v_ashrrev_i32_e32 v39, 31, v38
	v_pk_add_f32 v[36:37], v[36:37], v[40:41]
	v_lshlrev_b64 v[38:39], 13, v[38:39]
	global_store_dwordx4 v[42:43], v[34:37], off
	v_lshl_add_u64 v[42:43], v[96:97], 0, v[38:39]
	ds_read_b128 v[34:37], v98
	s_waitcnt vmcnt(7) lgkmcnt(0)
; DEV void store_tile_f32_add(const f32x4 (&acc)[8][4], const float* xres, float* out, int m0, int n0, unsigned char* smem) {
;     ...
; #pragma unroll
;   for (int mq = 0; mq < 4; ++mq) {
; #pragma unroll
;     for (int mh = 0; mh < 2; ++mh)
; #pragma unroll
;       for (int ni = 0; ni < 4; ++ni)
; #pragma unroll
;         for (int j = 0; j < 4; ++j) st[(mh * 16 + fq * 4 + j) * 68 + ni * 16 + fr] = acc[mq * 2 + mh][ni][j];
; #pragma unroll
;     for (int itr = 0; itr < 8; ++itr) {
;       const int rl = (lane >> 4) + 4 * itr;
;       const f32x4 v = *(const f32x4*)(st + rl * 68 + chunk * 4);
;       const size_t idx = (size_t)(m0 + wr * 128 + mq * 32 + rl) * 2048 + n0 + wc * 64 + chunk * 4;
;       const f32x4 x = *(const f32x4*)(xres + idx);
;       *(f32x4*)(out + idx) = x + v;
;     }
	v_mov_b64_e32 v[38:39], v[208:209]
	v_mov_b64_e32 v[40:41], v[210:211]
	v_pk_add_f32 v[34:35], v[34:35], v[38:39]
	v_or_b32_e32 v38, v32, v104
	v_ashrrev_i32_e32 v39, 31, v38
	v_pk_add_f32 v[36:37], v[36:37], v[40:41]
	v_lshlrev_b64 v[38:39], 13, v[38:39]
	global_store_dwordx4 v[42:43], v[34:37], off
	v_lshl_add_u64 v[42:43], v[96:97], 0, v[38:39]
	ds_read_b128 v[34:37], v98 offset:1088
	s_waitcnt vmcnt(7) lgkmcnt(0)
	v_mov_b64_e32 v[38:39], v[212:213]
	v_mov_b64_e32 v[40:41], v[214:215]
	v_pk_add_f32 v[34:35], v[34:35], v[38:39]
	v_or_b32_e32 v38, v32, v105
	v_ashrrev_i32_e32 v39, 31, v38
	v_pk_add_f32 v[36:37], v[36:37], v[40:41]
	v_lshlrev_b64 v[38:39], 13, v[38:39]
	global_store_dwordx4 v[42:43], v[34:37], off
	v_lshl_add_u64 v[42:43], v[96:97], 0, v[38:39]
	ds_read_b128 v[34:37], v98 offset:2176
	s_waitcnt vmcnt(7) lgkmcnt(0)
	v_mov_b64_e32 v[38:39], v[216:217]
	v_mov_b64_e32 v[40:41], v[218:219]
	v_pk_add_f32 v[34:35], v[34:35], v[38:39]
	v_or_b32_e32 v38, v32, v106
	v_ashrrev_i32_e32 v39, 31, v38
	v_pk_add_f32 v[36:37], v[36:37], v[40:41]
	v_lshlrev_b64 v[38:39], 13, v[38:39]
	global_store_dwordx4 v[42:43], v[34:37], off
	v_lshl_add_u64 v[42:43], v[96:97], 0, v[38:39]
	ds_read_b128 v[34:37], v98 offset:3264
	s_waitcnt vmcnt(7) lgkmcnt(0)
	v_mov_b64_e32 v[38:39], v[220:221]
	v_mov_b64_e32 v[40:41], v[222:223]
	v_pk_add_f32 v[34:35], v[34:35], v[38:39]
	v_or_b32_e32 v38, v32, v107
	v_ashrrev_i32_e32 v39, 31, v38
	v_pk_add_f32 v[36:37], v[36:37], v[40:41]
	v_lshlrev_b64 v[38:39], 13, v[38:39]
	global_store_dwordx4 v[42:43], v[34:37], off
	v_lshl_add_u64 v[42:43], v[96:97], 0, v[38:39]
	ds_read_b128 v[34:37], v98 offset:4352
	s_waitcnt vmcnt(7) lgkmcnt(0)
	v_mov_b64_e32 v[38:39], v[224:225]
	v_mov_b64_e32 v[40:41], v[226:227]
	v_pk_add_f32 v[34:35], v[34:35], v[38:39]
	v_or_b32_e32 v38, v32, v108
	v_ashrrev_i32_e32 v39, 31, v38
	v_pk_add_f32 v[36:37], v[36:37], v[40:41]
	v_lshlrev_b64 v[38:39], 13, v[38:39]
	global_store_dwordx4 v[42:43], v[34:37], off
	v_lshl_add_u64 v[42:43], v[96:97], 0, v[38:39]
	ds_read_b128 v[34:37], v98 offset:5440
	v_or_b32_e32 v32, v32, v109
	v_ashrrev_i32_e32 v33, 31, v32
	v_lshlrev_b64 v[32:33], 13, v[32:33]
	v_lshl_add_u64 v[32:33], v[96:97], 0, v[32:33]
	s_waitcnt vmcnt(7) lgkmcnt(0)
	v_mov_b64_e32 v[38:39], v[232:233]
	v_mov_b64_e32 v[40:41], v[234:235]
	v_pk_add_f32 v[36:37], v[36:37], v[40:41]
	v_pk_add_f32 v[34:35], v[34:35], v[38:39]
	s_nop 0
	global_store_dwordx4 v[42:43], v[34:37], off
	ds_read_b128 v[34:37], v98 offset:6528
	s_waitcnt vmcnt(7) lgkmcnt(0)
	v_mov_b64_e32 v[38:39], v[236:237]
	v_mov_b64_e32 v[40:41], v[238:239]
	v_pk_add_f32 v[36:37], v[36:37], v[40:41]
	v_pk_add_f32 v[34:35], v[34:35], v[38:39]
	global_store_dwordx4 v[32:33], v[34:37], off
	ds_write_b32 v103, v28
	ds_write_b32 v103, v29 offset:272
	ds_write_b32 v103, v30 offset:544
	ds_write_b32 v103, v31 offset:816
	ds_write_b32 v103, v24 offset:64
	ds_write_b32 v103, v25 offset:336
	ds_write_b32 v103, v26 offset:608
	ds_write_b32 v103, v27 offset:880
	ds_write_b32 v103, v20 offset:128
	ds_write_b32 v103, v21 offset:400
	ds_write_b32 v103, v22 offset:672
	ds_write_b32 v103, v23 offset:944
	ds_write_b32 v103, v16 offset:192
	ds_write_b32 v103, v17 offset:464
	ds_write_b32 v103, v18 offset:736
	ds_write_b32 v103, v19 offset:1008
	ds_write_b32 v103, v12 offset:4352
	ds_write_b32 v103, v13 offset:4624
	ds_write_b32 v103, v14 offset:4896
	ds_write_b32 v103, v15 offset:5168
	ds_write_b32 v103, v8 offset:4416
	ds_write_b32 v103, v9 offset:4688
	ds_write_b32 v103, v10 offset:4960
	ds_write_b32 v103, v11 offset:5232
	ds_write_b32 v103, v4 offset:4480
	ds_write_b32 v103, v5 offset:4752
	ds_write_b32 v103, v6 offset:5024
	ds_write_b32 v103, v7 offset:5296
	ds_write_b32 v103, v0 offset:4544
	ds_write_b32 v103, v1 offset:4816
	ds_write_b32 v103, v2 offset:5088
	ds_write_b32 v103, v3 offset:5360
	v_or_b32_e32 v10, 0x60, v101
	v_or_b32_e32 v4, v10, v100
	v_ashrrev_i32_e32 v5, 31, v4
	v_lshlrev_b64 v[4:5], 13, v[4:5]
	v_lshl_add_u64 v[8:9], v[96:97], 0, v[4:5]
	v_mov_b32_e32 v242, 0x8000
	v_mov_b32_e32 v243, 0
	v_mov_b64_e32 v[240:241], v[8:9]
	global_load_dwordx4 v[4:7], v[8:9], off
	v_lshl_add_u64 v[240:241], v[240:241], 0, v[242:243]
	global_load_dwordx4 v[208:211], v[240:241], off
	v_lshl_add_u64 v[240:241], v[240:241], 0, v[242:243]
	global_load_dwordx4 v[212:215], v[240:241], off
	v_lshl_add_u64 v[240:241], v[240:241], 0, v[242:243]
	global_load_dwordx4 v[216:219], v[240:241], off
	v_lshl_add_u64 v[240:241], v[240:241], 0, v[242:243]
	global_load_dwordx4 v[220:223], v[240:241], off
	v_lshl_add_u64 v[240:241], v[240:241], 0, v[242:243]
	global_load_dwordx4 v[224:227], v[240:241], off
	v_lshl_add_u64 v[240:241], v[240:241], 0, v[242:243]
	global_load_dwordx4 v[232:235], v[240:241], off
	v_lshl_add_u64 v[240:241], v[240:241], 0, v[242:243]
	global_load_dwordx4 v[236:239], v[240:241], off
	ds_read_b128 v[0:3], v102
	s_waitcnt vmcnt(7) lgkmcnt(0)
; DEV void store_tile_f32_add(const f32x4 (&acc)[8][4], const float* xres, float* out, int m0, int n0, unsigned char* smem) {
;     ...
; #pragma unroll
;     for (int itr = 0; itr < 8; ++itr) {
;       const int rl = (lane >> 4) + 4 * itr;
;       const f32x4 v = *(const f32x4*)(st + rl * 68 + chunk * 4);
;       const size_t idx = (size_t)(m0 + wr * 128 + mq * 32 + rl) * 2048 + n0 + wc * 64 + chunk * 4;
;       const f32x4 x = *(const f32x4*)(xres + idx);
;       *(f32x4*)(out + idx) = x + v;
;     }
	v_pk_add_f32 v[0:1], v[0:1], v[4:5]
	v_or_b32_e32 v4, v10, v99
	v_ashrrev_i32_e32 v5, 31, v4
	v_pk_add_f32 v[2:3], v[2:3], v[6:7]
	v_lshlrev_b64 v[4:5], 13, v[4:5]
	global_store_dwordx4 v[8:9], v[0:3], off
	v_lshl_add_u64 v[8:9], v[96:97], 0, v[4:5]
	ds_read_b128 v[0:3], v98
	s_waitcnt vmcnt(7) lgkmcnt(0)
	v_mov_b64_e32 v[4:5], v[208:209]
	v_mov_b64_e32 v[6:7], v[210:211]
	v_pk_add_f32 v[0:1], v[0:1], v[4:5]
	v_or_b32_e32 v4, v10, v104
	v_ashrrev_i32_e32 v5, 31, v4
	v_pk_add_f32 v[2:3], v[2:3], v[6:7]
	v_lshlrev_b64 v[4:5], 13, v[4:5]
	global_store_dwordx4 v[8:9], v[0:3], off
	v_lshl_add_u64 v[8:9], v[96:97], 0, v[4:5]
	ds_read_b128 v[0:3], v98 offset:1088
	s_waitcnt vmcnt(7) lgkmcnt(0)
	v_mov_b64_e32 v[4:5], v[212:213]
	v_mov_b64_e32 v[6:7], v[214:215]
	v_pk_add_f32 v[0:1], v[0:1], v[4:5]
	v_or_b32_e32 v4, v10, v105
	v_ashrrev_i32_e32 v5, 31, v4
	v_pk_add_f32 v[2:3], v[2:3], v[6:7]
	v_lshlrev_b64 v[4:5], 13, v[4:5]
	global_store_dwordx4 v[8:9], v[0:3], off
	v_lshl_add_u64 v[8:9], v[96:97], 0, v[4:5]
	ds_read_b128 v[0:3], v98 offset:2176
	s_waitcnt vmcnt(7) lgkmcnt(0)
	v_mov_b64_e32 v[4:5], v[216:217]
	v_mov_b64_e32 v[6:7], v[218:219]
	v_pk_add_f32 v[0:1], v[0:1], v[4:5]
	v_or_b32_e32 v4, v10, v106
	v_ashrrev_i32_e32 v5, 31, v4
	v_pk_add_f32 v[2:3], v[2:3], v[6:7]
	v_lshlrev_b64 v[4:5], 13, v[4:5]
	global_store_dwordx4 v[8:9], v[0:3], off
	v_lshl_add_u64 v[8:9], v[96:97], 0, v[4:5]
	ds_read_b128 v[0:3], v98 offset:3264
	s_waitcnt vmcnt(7) lgkmcnt(0)
	v_mov_b64_e32 v[4:5], v[220:221]
	v_mov_b64_e32 v[6:7], v[222:223]
	v_pk_add_f32 v[0:1], v[0:1], v[4:5]
	v_or_b32_e32 v4, v10, v107
	v_ashrrev_i32_e32 v5, 31, v4
	v_pk_add_f32 v[2:3], v[2:3], v[6:7]
	v_lshlrev_b64 v[4:5], 13, v[4:5]
	global_store_dwordx4 v[8:9], v[0:3], off
	v_lshl_add_u64 v[8:9], v[96:97], 0, v[4:5]
	ds_read_b128 v[0:3], v98 offset:4352
	s_waitcnt vmcnt(7) lgkmcnt(0)
	v_mov_b64_e32 v[4:5], v[224:225]
	v_mov_b64_e32 v[6:7], v[226:227]
	v_pk_add_f32 v[0:1], v[0:1], v[4:5]
	v_or_b32_e32 v4, v10, v108
	v_ashrrev_i32_e32 v5, 31, v4
	v_pk_add_f32 v[2:3], v[2:3], v[6:7]
	v_lshlrev_b64 v[4:5], 13, v[4:5]
	global_store_dwordx4 v[8:9], v[0:3], off
	v_lshl_add_u64 v[8:9], v[96:97], 0, v[4:5]
	ds_read_b128 v[0:3], v98 offset:5440
	s_waitcnt vmcnt(7) lgkmcnt(0)
	v_mov_b64_e32 v[4:5], v[232:233]
	v_mov_b64_e32 v[6:7], v[234:235]
	v_pk_add_f32 v[0:1], v[0:1], v[4:5]
	v_or_b32_e32 v4, v10, v109
	v_ashrrev_i32_e32 v5, 31, v4
	v_pk_add_f32 v[2:3], v[2:3], v[6:7]
	v_lshlrev_b64 v[4:5], 13, v[4:5]
	global_store_dwordx4 v[8:9], v[0:3], off
	v_lshl_add_u64 v[8:9], v[96:97], 0, v[4:5]
	ds_read_b128 v[0:3], v98 offset:6528
	s_waitcnt vmcnt(7) lgkmcnt(0)
	v_mov_b64_e32 v[4:5], v[236:237]
	v_mov_b64_e32 v[6:7], v[238:239]
	v_pk_add_f32 v[2:3], v[2:3], v[6:7]
	v_pk_add_f32 v[0:1], v[0:1], v[4:5]
	global_store_dwordx4 v[8:9], v[0:3], off
	s_branch .LBB0_191

; DEV f32x4 mfma16(bf16x8 a, bf16x8 b, f32x4 c) { return __builtin_amdgcn_mfma_f32_16x16x32_bf16(a, b, c, 0, 0, 0); }
; DEV void gemm_tile(const u16* __restrict__ A, size_t lda, const u16* __restrict__ Bt, size_t ldb, int K,
;                    u16* sA, u16* sB, f32x4 (&acc)[8][4]) {
;     ...
;   for (int kt = 0; kt < nk; ++kt) {
;     const int st = kt & 1;
;     if (kt + 1 < nk) S_STORE(st ^ 1)
;     if (kt + 2 < nk) G_LOAD((kt + 2) << 5)
;     {
;       const u16* pa = sAr + st * 12288;
;       const u16* pb = sBr + st * 12288;
;       bf16x8 b[4];
; #pragma unroll
;       for (int ni = 0; ni < 4; ++ni) b[ni] = *(const bf16x8*)(pb + ni * 16 * 32);
; #pragma unroll
;       for (int mh = 0; mh < 2; ++mh) {
;         bf16x8 a[4];
; #pragma unroll
;         for (int mi = 0; mi < 4; ++mi) a[mi] = *(const bf16x8*)(pa + (mh * 64 + mi * 16) * 32);
; #pragma unroll
;         for (int mi = 0; mi < 4; ++mi)
; #pragma unroll
;           for (int ni = 0; ni < 4; ++ni) acc[mh * 4 + mi][ni] = mfma16(a[mi], b[ni], acc[mh * 4 + mi][ni]);
;       }
;     }
;     __syncthreads();
;   }
.LBB0_251:
	v_add_u32_e32 v229, s8, v163
	v_add_u32_e32 v228, s8, v162
	ds_read_b128 v[124:127], v229 offset:16384
	ds_read_b128 v[166:169], v228
	ds_read_b128 v[132:135], v229 offset:17408
	ds_read_b128 v[144:147], v229 offset:18432
	ds_read_b128 v[128:131], v229 offset:19456
	ds_read_b128 v[152:155], v228 offset:1024
	ds_read_b128 v[170:173], v228 offset:2048
	ds_read_b128 v[136:139], v228 offset:3072
	s_waitcnt lgkmcnt(6)
	v_mfma_f32_16x16x32_bf16 v[148:151], v[166:169], v[124:127], v[148:151]
	s_waitcnt lgkmcnt(5)
	v_mfma_f32_16x16x32_bf16 v[120:123], v[166:169], v[132:135], v[120:123]
	s_waitcnt lgkmcnt(4)
	v_mfma_f32_16x16x32_bf16 v[116:119], v[166:169], v[144:147], v[116:119]
	s_waitcnt lgkmcnt(3)
	v_mfma_f32_16x16x32_bf16 v[112:115], v[166:169], v[128:131], v[112:115]
	ds_read_b128 v[232:235], v228 offset:4096
	ds_read_b128 v[236:239], v228 offset:5120
	s_waitcnt lgkmcnt(4)
	v_mfma_f32_16x16x32_bf16 v[108:111], v[152:155], v[124:127], v[108:111]
	s_add_i32 m0, s9, 0x0
	v_mfma_f32_16x16x32_bf16 v[104:107], v[152:155], v[132:135], v[104:107]
	global_load_lds_dwordx4 v[140:141], off
	v_lshl_add_u64 v[140:141], v[140:141], 0, 64
	global_load_dwordx4 v[244:247], v[140:141], off
	v_lshl_add_u64 v[140:141], v[140:141], 0, 64
	v_mfma_f32_16x16x32_bf16 v[100:103], v[152:155], v[144:147], v[100:103]
	s_add_i32 m0, s9, 0x1000
	v_mfma_f32_16x16x32_bf16 v[96:99], v[152:155], v[128:131], v[96:99]
	global_load_lds_dwordx4 v[142:143], off
	v_lshl_add_u64 v[142:143], v[142:143], 0, 64
	global_load_dwordx4 v[252:255], v[142:143], off
	v_lshl_add_u64 v[142:143], v[142:143], 0, 64
	s_waitcnt lgkmcnt(3)
	v_mfma_f32_16x16x32_bf16 v[92:95], v[170:173], v[124:127], v[92:95]
	s_add_i32 m0, s9, 0x2000
	v_mfma_f32_16x16x32_bf16 v[88:91], v[170:173], v[132:135], v[88:91]
	global_load_lds_dwordx4 v[174:175], off
	v_lshl_add_u64 v[174:175], v[174:175], 0, 64
	global_load_dwordx4 v[208:211], v[174:175], off
	v_lshl_add_u64 v[174:175], v[174:175], 0, 64
	v_mfma_f32_16x16x32_bf16 v[84:87], v[170:173], v[144:147], v[84:87]
	s_add_i32 m0, s9, 0x3000
	v_mfma_f32_16x16x32_bf16 v[80:83], v[170:173], v[128:131], v[80:83]
	ds_read_b128 v[240:243], v228 offset:6144
	ds_read_b128 v[166:169], v228 offset:7168
	s_waitcnt lgkmcnt(4)
	v_mfma_f32_16x16x32_bf16 v[76:79], v[136:139], v[124:127], v[76:79]
	global_load_lds_dwordx4 v[176:177], off
	v_lshl_add_u64 v[176:177], v[176:177], 0, 64
	global_load_dwordx4 v[212:215], v[176:177], off
	v_lshl_add_u64 v[176:177], v[176:177], 0, 64
	v_mfma_f32_16x16x32_bf16 v[72:75], v[136:139], v[132:135], v[72:75]
	s_add_i32 m0, s9, 0x4000
	v_mfma_f32_16x16x32_bf16 v[68:71], v[136:139], v[144:147], v[68:71]
	global_load_lds_dwordx4 v[186:187], off
	v_lshl_add_u64 v[186:187], v[186:187], 0, 64
	global_load_dwordx4 v[216:219], v[186:187], off
	v_lshl_add_u64 v[186:187], v[186:187], 0, 64
	v_mfma_f32_16x16x32_bf16 v[64:67], v[136:139], v[128:131], v[64:67]
	s_add_i32 m0, s9, 0x5000
	s_waitcnt lgkmcnt(3)
	v_mfma_f32_16x16x32_bf16 v[60:63], v[232:235], v[124:127], v[60:63]
	global_load_lds_dwordx4 v[188:189], off
	v_lshl_add_u64 v[188:189], v[188:189], 0, 64
	global_load_dwordx4 v[220:223], v[188:189], off
	v_lshl_add_u64 v[188:189], v[188:189], 0, 64
	v_mfma_f32_16x16x32_bf16 v[56:59], v[232:235], v[132:135], v[56:59]
	s_add_i32 s9, s8, s5
	s_add_i32 s8, s8, 0x6000
	v_mfma_f32_16x16x32_bf16 v[52:55], v[232:235], v[144:147], v[52:55]
	s_cmp_eq_u32 s8, 0x12000
	s_cselect_b32 s8, 0, s8
	v_mfma_f32_16x16x32_bf16 v[48:51], v[232:235], v[128:131], v[48:51]
	s_add_u32 s6, s6, 64
	s_addc_u32 s7, s7, 0
	s_cmpk_lg_i32 s6, 0xf80
	s_waitcnt lgkmcnt(2)
	v_mfma_f32_16x16x32_bf16 v[44:47], v[236:239], v[124:127], v[44:47]
	v_mfma_f32_16x16x32_bf16 v[40:43], v[236:239], v[132:135], v[40:43]
	v_mfma_f32_16x16x32_bf16 v[36:39], v[236:239], v[144:147], v[36:39]
	v_mfma_f32_16x16x32_bf16 v[32:35], v[236:239], v[128:131], v[32:35]
	s_waitcnt lgkmcnt(1)
	v_mfma_f32_16x16x32_bf16 v[28:31], v[240:243], v[124:127], v[28:31]
	v_mfma_f32_16x16x32_bf16 v[24:27], v[240:243], v[132:135], v[24:27]
	v_mfma_f32_16x16x32_bf16 v[20:23], v[240:243], v[144:147], v[20:23]
	v_mfma_f32_16x16x32_bf16 v[16:19], v[240:243], v[128:131], v[16:19]
	s_waitcnt lgkmcnt(0)
	s_waitcnt vmcnt(12)
	s_barrier
	v_mfma_f32_16x16x32_bf16 v[12:15], v[166:169], v[124:127], v[12:15]
	v_mfma_f32_16x16x32_bf16 v[8:11], v[166:169], v[132:135], v[8:11]
	v_mfma_f32_16x16x32_bf16 v[4:7], v[166:169], v[144:147], v[4:7]
	v_mfma_f32_16x16x32_bf16 v[0:3], v[166:169], v[128:131], v[0:3]
	v_add_u32_e32 v229, s8, v163
	v_add_u32_e32 v228, s8, v162
	ds_read_b128 v[124:127], v229 offset:16384
	ds_read_b128 v[166:169], v228
	ds_read_b128 v[132:135], v229 offset:17408
	ds_read_b128 v[144:147], v229 offset:18432
	ds_read_b128 v[128:131], v229 offset:19456
	ds_read_b128 v[152:155], v228 offset:1024
	ds_read_b128 v[170:173], v228 offset:2048
	ds_read_b128 v[136:139], v228 offset:3072
	s_waitcnt lgkmcnt(6)
	v_mfma_f32_16x16x32_bf16 v[148:151], v[166:169], v[124:127], v[148:151]
	s_waitcnt lgkmcnt(5)
	v_mfma_f32_16x16x32_bf16 v[120:123], v[166:169], v[132:135], v[120:123]
	s_waitcnt lgkmcnt(4)
	v_mfma_f32_16x16x32_bf16 v[116:119], v[166:169], v[144:147], v[116:119]
	s_waitcnt lgkmcnt(3)
	v_mfma_f32_16x16x32_bf16 v[112:115], v[166:169], v[128:131], v[112:115]
	ds_read_b128 v[232:235], v228 offset:4096
	ds_read_b128 v[236:239], v228 offset:5120
	s_waitcnt lgkmcnt(4)
	v_mfma_f32_16x16x32_bf16 v[108:111], v[152:155], v[124:127], v[108:111]
	v_mfma_f32_16x16x32_bf16 v[104:107], v[152:155], v[132:135], v[104:107]
	v_mfma_f32_16x16x32_bf16 v[100:103], v[152:155], v[144:147], v[100:103]
	v_mfma_f32_16x16x32_bf16 v[96:99], v[152:155], v[128:131], v[96:99]
	s_waitcnt lgkmcnt(3)
; DEV f32x4 mfma16(bf16x8 a, bf16x8 b, f32x4 c) { return __builtin_amdgcn_mfma_f32_16x16x32_bf16(a, b, c, 0, 0, 0); }
; DEV void gemm_tile(const u16* __restrict__ A, size_t lda, const u16* __restrict__ Bt, size_t ldb, int K,
;                    u16* sA, u16* sB, f32x4 (&acc)[8][4]) {
;     ...
;   for (int kt = 0; kt < nk; ++kt) {
;     const int st = kt & 1;
;     if (kt + 1 < nk) S_STORE(st ^ 1)
;     if (kt + 2 < nk) G_LOAD((kt + 2) << 5)
;     {
;       const u16* pa = sAr + st * 12288;
;       const u16* pb = sBr + st * 12288;
;       bf16x8 b[4];
; #pragma unroll
;       for (int ni = 0; ni < 4; ++ni) b[ni] = *(const bf16x8*)(pb + ni * 16 * 32);
; #pragma unroll
;       for (int mh = 0; mh < 2; ++mh) {
;         bf16x8 a[4];
; #pragma unroll
;         for (int mi = 0; mi < 4; ++mi) a[mi] = *(const bf16x8*)(pa + (mh * 64 + mi * 16) * 32);
; #pragma unroll
;         for (int mi = 0; mi < 4; ++mi)
; #pragma unroll
;           for (int ni = 0; ni < 4; ++ni) acc[mh * 4 + mi][ni] = mfma16(a[mi], b[ni], acc[mh * 4 + mi][ni]);
;       }
;     }
;     __syncthreads();
;   }
	v_mfma_f32_16x16x32_bf16 v[92:95], v[170:173], v[124:127], v[92:95]
	v_mfma_f32_16x16x32_bf16 v[88:91], v[170:173], v[132:135], v[88:91]
	v_mfma_f32_16x16x32_bf16 v[84:87], v[170:173], v[144:147], v[84:87]
	v_mfma_f32_16x16x32_bf16 v[80:83], v[170:173], v[128:131], v[80:83]
	ds_read_b128 v[240:243], v228 offset:6144
	ds_read_b128 v[166:169], v228 offset:7168
	s_waitcnt lgkmcnt(4)
	v_mfma_f32_16x16x32_bf16 v[76:79], v[136:139], v[124:127], v[76:79]
	s_waitcnt vmcnt(0)
	v_add_u32_e32 v231, s9, v230
	v_mfma_f32_16x16x32_bf16 v[72:75], v[136:139], v[132:135], v[72:75]
	ds_write_b128 v231, v[244:247]
	v_mfma_f32_16x16x32_bf16 v[68:71], v[136:139], v[144:147], v[68:71]
	ds_write_b128 v231, v[252:255] offset:4096
	v_mfma_f32_16x16x32_bf16 v[64:67], v[136:139], v[128:131], v[64:67]
	ds_write_b128 v231, v[208:211] offset:8192
	s_waitcnt lgkmcnt(6)
	v_mfma_f32_16x16x32_bf16 v[60:63], v[232:235], v[124:127], v[60:63]
	ds_write_b128 v231, v[212:215] offset:12288
	v_mfma_f32_16x16x32_bf16 v[56:59], v[232:235], v[132:135], v[56:59]
	ds_write_b128 v231, v[216:219] offset:16384
	v_mfma_f32_16x16x32_bf16 v[52:55], v[232:235], v[144:147], v[52:55]
	ds_write_b128 v231, v[220:223] offset:20480
	v_mfma_f32_16x16x32_bf16 v[48:51], v[232:235], v[128:131], v[48:51]
	s_add_i32 s9, s8, s5
	s_add_i32 s8, s8, 0x6000
	s_waitcnt lgkmcnt(8)
	v_mfma_f32_16x16x32_bf16 v[44:47], v[236:239], v[124:127], v[44:47]
	s_cmp_eq_u32 s8, 0x12000
	s_cselect_b32 s8, 0, s8
	v_mfma_f32_16x16x32_bf16 v[40:43], v[236:239], v[132:135], v[40:43]
	s_add_u32 s6, s6, 64
	s_addc_u32 s7, s7, 0
	s_cmpk_lg_i32 s6, 0xf80
	v_mfma_f32_16x16x32_bf16 v[36:39], v[236:239], v[144:147], v[36:39]
	v_mfma_f32_16x16x32_bf16 v[32:35], v[236:239], v[128:131], v[32:35]
	s_waitcnt lgkmcnt(7)
	v_mfma_f32_16x16x32_bf16 v[28:31], v[240:243], v[124:127], v[28:31]
	v_mfma_f32_16x16x32_bf16 v[24:27], v[240:243], v[132:135], v[24:27]
	v_mfma_f32_16x16x32_bf16 v[20:23], v[240:243], v[144:147], v[20:23]
	v_mfma_f32_16x16x32_bf16 v[16:19], v[240:243], v[128:131], v[16:19]
	s_waitcnt lgkmcnt(6)
	s_waitcnt lgkmcnt(0)
	s_barrier
	v_mfma_f32_16x16x32_bf16 v[12:15], v[166:169], v[124:127], v[12:15]
	v_mfma_f32_16x16x32_bf16 v[8:11], v[166:169], v[132:135], v[8:11]
	v_mfma_f32_16x16x32_bf16 v[4:7], v[166:169], v[144:147], v[4:7]
	v_mfma_f32_16x16x32_bf16 v[0:3], v[166:169], v[128:131], v[0:3]
	s_cbranch_scc1 .LBB0_251
	ds_read_b128 v[124:127], v163 offset:16384
	ds_read_b128 v[128:131], v163 offset:17408
	ds_read_b128 v[132:135], v163 offset:18432
	ds_read_b128 v[136:139], v163 offset:19456
	ds_read_b128 v[140:143], v162
	ds_read_b128 v[144:147], v162 offset:1024
	ds_read_b128 v[152:155], v162 offset:2048
	ds_read_b128 v[158:161], v162 offset:3072
	s_movk_i32 s5, 0x2200
	s_waitcnt lgkmcnt(3)
	v_mfma_f32_16x16x32_bf16 v[148:151], v[140:143], v[124:127], v[148:151]
	v_mfma_f32_16x16x32_bf16 v[120:123], v[140:143], v[128:131], v[120:123]
	v_mfma_f32_16x16x32_bf16 v[116:119], v[140:143], v[132:135], v[116:119]
	v_mfma_f32_16x16x32_bf16 v[112:115], v[140:143], v[136:139], v[112:115]
	s_waitcnt lgkmcnt(2)
	v_mfma_f32_16x16x32_bf16 v[108:111], v[144:147], v[124:127], v[108:111]
	v_mfma_f32_16x16x32_bf16 v[104:107], v[144:147], v[128:131], v[104:107]
	v_mfma_f32_16x16x32_bf16 v[100:103], v[144:147], v[132:135], v[100:103]
	v_mfma_f32_16x16x32_bf16 v[96:99], v[144:147], v[136:139], v[96:99]
	s_waitcnt lgkmcnt(1)
	v_mfma_f32_16x16x32_bf16 v[92:95], v[152:155], v[124:127], v[92:95]
	v_mfma_f32_16x16x32_bf16 v[88:91], v[152:155], v[128:131], v[88:91]
	v_mfma_f32_16x16x32_bf16 v[84:87], v[152:155], v[132:135], v[84:87]
	v_mfma_f32_16x16x32_bf16 v[80:83], v[152:155], v[136:139], v[80:83]
	s_waitcnt lgkmcnt(0)
	v_mfma_f32_16x16x32_bf16 v[76:79], v[158:161], v[124:127], v[76:79]
	v_mfma_f32_16x16x32_bf16 v[72:75], v[158:161], v[128:131], v[72:75]
	v_mfma_f32_16x16x32_bf16 v[68:71], v[158:161], v[132:135], v[68:71]
	v_mfma_f32_16x16x32_bf16 v[64:67], v[158:161], v[136:139], v[64:67]
	ds_read_b128 v[140:143], v162 offset:4096
	ds_read_b128 v[144:147], v162 offset:5120
	ds_read_b128 v[152:155], v162 offset:6144
	ds_read_b128 v[158:161], v162 offset:7168
	s_waitcnt lgkmcnt(0)
	s_waitcnt vmcnt(0)
	s_barrier
	v_mfma_f32_16x16x32_bf16 v[60:63], v[140:143], v[124:127], v[60:63]
	v_mfma_f32_16x16x32_bf16 v[56:59], v[140:143], v[128:131], v[56:59]
	v_mfma_f32_16x16x32_bf16 v[52:55], v[140:143], v[132:135], v[52:55]
	v_mfma_f32_16x16x32_bf16 v[48:51], v[140:143], v[136:139], v[48:51]
	v_mfma_f32_16x16x32_bf16 v[44:47], v[144:147], v[124:127], v[44:47]
	v_mfma_f32_16x16x32_bf16 v[40:43], v[144:147], v[128:131], v[40:43]
	v_mfma_f32_16x16x32_bf16 v[36:39], v[144:147], v[132:135], v[36:39]
	v_mfma_f32_16x16x32_bf16 v[32:35], v[144:147], v[136:139], v[32:35]
	v_mfma_f32_16x16x32_bf16 v[28:31], v[152:155], v[124:127], v[28:31]
	v_mfma_f32_16x16x32_bf16 v[24:27], v[152:155], v[128:131], v[24:27]
	v_mfma_f32_16x16x32_bf16 v[20:23], v[152:155], v[132:135], v[20:23]
	v_mfma_f32_16x16x32_bf16 v[16:19], v[152:155], v[136:139], v[16:19]
	v_mfma_f32_16x16x32_bf16 v[12:15], v[158:161], v[124:127], v[12:15]
	v_mfma_f32_16x16x32_bf16 v[8:11], v[158:161], v[128:131], v[8:11]
	v_mfma_f32_16x16x32_bf16 v[4:7], v[158:161], v[132:135], v[4:7]
	v_mfma_f32_16x16x32_bf16 v[0:3], v[158:161], v[136:139], v[0:3]
	ds_read_b128 v[124:127], v163 offset:40960
	ds_read_b128 v[128:131], v163 offset:41984
	ds_read_b128 v[132:135], v163 offset:43008
	ds_read_b128 v[136:139], v163 offset:44032
	ds_read_b128 v[140:143], v162 offset:24576
	ds_read_b128 v[144:147], v162 offset:25600
	ds_read_b128 v[152:155], v162 offset:26624
	ds_read_b128 v[158:161], v162 offset:27648
	s_waitcnt lgkmcnt(3)
	v_mfma_f32_16x16x32_bf16 v[148:151], v[140:143], v[124:127], v[148:151]
	v_mfma_f32_16x16x32_bf16 v[120:123], v[140:143], v[128:131], v[120:123]
	v_mfma_f32_16x16x32_bf16 v[116:119], v[140:143], v[132:135], v[116:119]
	v_mfma_f32_16x16x32_bf16 v[112:115], v[140:143], v[136:139], v[112:115]
	s_waitcnt lgkmcnt(2)
	v_mfma_f32_16x16x32_bf16 v[108:111], v[144:147], v[124:127], v[108:111]
	v_mfma_f32_16x16x32_bf16 v[140:143], v[144:147], v[128:131], v[104:107]
	v_mfma_f32_16x16x32_bf16 v[164:167], v[144:147], v[132:135], v[100:103]
	v_mfma_f32_16x16x32_bf16 v[96:99], v[144:147], v[136:139], v[96:99]
	s_waitcnt lgkmcnt(1)
	v_mfma_f32_16x16x32_bf16 v[92:95], v[152:155], v[124:127], v[92:95]
	v_mfma_f32_16x16x32_bf16 v[88:91], v[152:155], v[128:131], v[88:91]
	v_mfma_f32_16x16x32_bf16 v[84:87], v[152:155], v[132:135], v[84:87]
	v_mfma_f32_16x16x32_bf16 v[80:83], v[152:155], v[136:139], v[80:83]
	ds_read_b128 v[100:103], v162 offset:28672
	ds_read_b128 v[104:107], v162 offset:29696
	ds_read_b128 v[144:147], v162 offset:30720
	ds_read_b128 v[152:155], v162 offset:31744
	s_waitcnt lgkmcnt(0)
	s_barrier
; DEV f32x4 mfma16(bf16x8 a, bf16x8 b, f32x4 c) { return __builtin_amdgcn_mfma_f32_16x16x32_bf16(a, b, c, 0, 0, 0); }
; DEV void gemm_tile(const u16* __restrict__ A, size_t lda, const u16* __restrict__ Bt, size_t ldb, int K,
;                    u16* sA, u16* sB, f32x4 (&acc)[8][4]) {
;     ...
;         for (int mi = 0; mi < 4; ++mi) a[mi] = *(const bf16x8*)(pa + (mh * 64 + mi * 16) * 32);
; #pragma unroll
;         for (int mi = 0; mi < 4; ++mi)
; #pragma unroll
;           for (int ni = 0; ni < 4; ++ni) acc[mh * 4 + mi][ni] = mfma16(a[mi], b[ni], acc[mh * 4 + mi][ni]);
; DEV void store_tile_f32_add(const f32x4 (&acc)[8][4], const float* xres, float* out, int m0, int n0, unsigned char* smem) {
;     ...
;   const int chunk = lane & 15;
; #pragma unroll
;   for (int mq = 0; mq < 4; ++mq) {
; #pragma unroll
;     for (int mh = 0; mh < 2; ++mh)
; #pragma unroll
;       for (int ni = 0; ni < 4; ++ni)
; #pragma unroll
;         for (int j = 0; j < 4; ++j) st[(mh * 16 + fq * 4 + j) * 68 + ni * 16 + fr] = acc[mq * 2 + mh][ni][j];
; #pragma unroll
;     for (int itr = 0; itr < 8; ++itr) {
;       const int rl = (lane >> 4) + 4 * itr;
;       const f32x4 v = *(const f32x4*)(st + rl * 68 + chunk * 4);
;       const size_t idx = (size_t)(m0 + wr * 128 + mq * 32 + rl) * 2048 + n0 + wc * 64 + chunk * 4;
;       const f32x4 x = *(const f32x4*)(xres + idx);
;       *(f32x4*)(out + idx) = x + v;
;     }
	v_mfma_f32_16x16x32_bf16 v[60:63], v[100:103], v[124:127], v[60:63]
	v_mfma_f32_16x16x32_bf16 v[56:59], v[100:103], v[128:131], v[56:59]
	v_mfma_f32_16x16x32_bf16 v[52:55], v[100:103], v[132:135], v[52:55]
	v_mfma_f32_16x16x32_bf16 v[48:51], v[100:103], v[136:139], v[48:51]
	v_mov_b32_e32 v100, v178
	s_nop 0
	v_lshrrev_b32_e32 v101, 6, v100
	v_and_b32_e32 v103, 15, v100
	v_mfma_f32_16x16x32_bf16 v[44:47], v[104:107], v[124:127], v[44:47]
	v_mul_lo_u32 v101, v101, s5
	v_bfe_u32 v102, v100, 4, 2
	v_mfma_f32_16x16x32_bf16 v[40:43], v[104:107], v[128:131], v[40:43]
	v_mfma_f32_16x16x32_bf16 v[36:39], v[104:107], v[132:135], v[36:39]
	v_mfma_f32_16x16x32_bf16 v[32:35], v[104:107], v[136:139], v[32:35]
	v_lshlrev_b32_e32 v104, 2, v103
	v_or_b32_e32 v105, v101, v104
	v_and_b32_e32 v101, 0xffffff80, v100
	v_mad_u32_u24 v107, v103, 12, v105
	v_add_u32_e32 v103, s4, v101
	v_mov_b32_e32 v101, s3
	s_movk_i32 s3, 0x440
	v_mad_u32_u24 v106, v102, s3, v105
	ds_write_b32 v106, v148
	ds_write_b32 v106, v149 offset:272
	ds_write_b32 v106, v150 offset:544
	ds_write_b32 v106, v151 offset:816
	ds_write_b32 v106, v120 offset:64
	ds_write_b32 v106, v121 offset:336
	ds_write_b32 v106, v122 offset:608
	ds_write_b32 v106, v123 offset:880
	ds_write_b32 v106, v116 offset:128
	ds_write_b32 v106, v117 offset:400
	ds_write_b32 v106, v118 offset:672
	ds_write_b32 v106, v119 offset:944
	ds_write_b32 v106, v112 offset:192
	ds_write_b32 v106, v113 offset:464
	ds_write_b32 v106, v114 offset:736
	ds_write_b32 v106, v115 offset:1008
	ds_write_b32 v106, v108 offset:4352
	ds_write_b32 v106, v109 offset:4624
	ds_write_b32 v106, v110 offset:4896
	ds_write_b32 v106, v111 offset:5168
	ds_write_b32 v106, v140 offset:4416
	ds_write_b32 v106, v141 offset:4688
	ds_write_b32 v106, v142 offset:4960
	ds_write_b32 v106, v143 offset:5232
	ds_write_b32 v106, v164 offset:4480
	ds_write_b32 v106, v165 offset:4752
	ds_write_b32 v106, v166 offset:5024
	ds_write_b32 v106, v167 offset:5296
	ds_write_b32 v106, v96 offset:4544
	ds_write_b32 v106, v97 offset:4816
	ds_write_b32 v106, v98 offset:5088
	ds_write_b32 v106, v99 offset:5360
	v_or_b32_e32 v108, v103, v102
	v_and_b32_e32 v100, 64, v100
	v_ashrrev_i32_e32 v109, 31, v108
	v_or3_b32 v100, v104, v100, s2
	v_lshlrev_b64 v[108:109], 11, v[108:109]
	v_lshl_add_u64 v[108:109], v[100:101], 0, v[108:109]
	v_lshlrev_b64 v[112:113], 2, v[108:109]
	v_lshl_add_u64 v[108:109], s[20:21], 0, v[112:113]
	v_mov_b32_e32 v242, 0x8000
	v_mov_b32_e32 v243, 0
	v_mov_b64_e32 v[240:241], v[108:109]
	global_load_dwordx4 v[108:111], v[108:109], off
	v_lshl_add_u64 v[240:241], v[240:241], 0, v[242:243]
	global_load_dwordx4 v[208:211], v[240:241], off
	v_lshl_add_u64 v[240:241], v[240:241], 0, v[242:243]
	global_load_dwordx4 v[212:215], v[240:241], off
	v_lshl_add_u64 v[240:241], v[240:241], 0, v[242:243]
	global_load_dwordx4 v[216:219], v[240:241], off
	v_lshl_add_u64 v[240:241], v[240:241], 0, v[242:243]
	global_load_dwordx4 v[220:223], v[240:241], off
	v_lshl_add_u64 v[240:241], v[240:241], 0, v[242:243]
	global_load_dwordx4 v[224:227], v[240:241], off
	v_lshl_add_u64 v[240:241], v[240:241], 0, v[242:243]
	global_load_dwordx4 v[232:235], v[240:241], off
	v_lshl_add_u64 v[240:241], v[240:241], 0, v[242:243]
	global_load_dwordx4 v[236:239], v[240:241], off
	s_movk_i32 s2, 0x110
	v_mad_u32_u24 v104, v102, s2, v107
	ds_read_b128 v[96:99], v104
	v_readlane_b32 s4, v251, 7
	v_readlane_b32 s6, v251, 9
	v_readlane_b32 s7, v251, 10
	v_or_b32_e32 v105, 20, v102
	v_mfma_f32_16x16x32_bf16 v[64:67], v[158:161], v[136:139], v[64:67]
	v_readlane_b32 s5, v251, 8
	s_waitcnt vmcnt(7) lgkmcnt(0)
	v_pk_add_f32 v[98:99], v[98:99], v[110:111]
	v_pk_add_f32 v[96:97], v[96:97], v[108:109]
	v_lshl_add_u64 v[108:109], s[6:7], 0, v[112:113]
	global_store_dwordx4 v[108:109], v[96:99], off
	v_or_b32_e32 v109, 4, v102
	v_or_b32_e32 v108, 28, v102
	v_or_b32_e32 v98, v109, v103
	v_ashrrev_i32_e32 v99, 31, v98
	v_lshlrev_b64 v[98:99], 11, v[98:99]
	v_lshl_add_u64 v[98:99], v[98:99], 0, v[100:101]
	v_lshlrev_b64 v[98:99], 2, v[98:99]
	v_lshl_add_u64 v[114:115], s[20:21], 0, v[98:99]
	v_mad_u32_u24 v96, v109, s2, v107
	ds_read_b128 v[110:113], v96
	v_lshl_add_u64 v[98:99], s[6:7], 0, v[98:99]
	v_or_b32_e32 v97, 8, v102
	v_or_b32_e32 v107, 24, v102
	v_mfma_f32_16x16x32_bf16 v[76:79], v[158:161], v[124:127], v[76:79]
	s_waitcnt vmcnt(7) lgkmcnt(0)
	v_mov_b64_e32 v[114:115], v[208:209]
	v_mov_b64_e32 v[116:117], v[210:211]
	v_pk_add_f32 v[112:113], v[112:113], v[116:117]
	v_pk_add_f32 v[110:111], v[110:111], v[114:115]
	global_store_dwordx4 v[98:99], v[110:113], off
	v_or_b32_e32 v98, v97, v103
	v_ashrrev_i32_e32 v99, 31, v98
	v_lshlrev_b64 v[98:99], 11, v[98:99]
	v_lshl_add_u64 v[98:99], v[98:99], 0, v[100:101]
	v_lshlrev_b64 v[98:99], 2, v[98:99]
	v_lshl_add_u64 v[114:115], s[20:21], 0, v[98:99]
	ds_read_b128 v[110:113], v96 offset:1088
	v_lshl_add_u64 v[98:99], s[6:7], 0, v[98:99]
	v_mfma_f32_16x16x32_bf16 v[72:75], v[158:161], v[128:131], v[72:75]
	s_waitcnt vmcnt(7) lgkmcnt(0)
	v_mov_b64_e32 v[114:115], v[212:213]
	v_mov_b64_e32 v[116:117], v[214:215]
	v_pk_add_f32 v[112:113], v[112:113], v[116:117]
	v_pk_add_f32 v[110:111], v[110:111], v[114:115]
	global_store_dwordx4 v[98:99], v[110:113], off
	v_or_b32_e32 v98, 12, v102
	v_or_b32_e32 v114, v98, v103
	v_ashrrev_i32_e32 v115, 31, v114
	v_lshlrev_b64 v[114:115], 11, v[114:115]
	v_lshl_add_u64 v[114:115], v[114:115], 0, v[100:101]
	v_lshlrev_b64 v[118:119], 2, v[114:115]
	v_lshl_add_u64 v[114:115], s[20:21], 0, v[118:119]
	ds_read_b128 v[110:113], v96 offset:2176
	v_or_b32_e32 v99, 16, v102
	v_mfma_f32_16x16x32_bf16 v[68:71], v[158:161], v[132:135], v[68:71]
	s_waitcnt vmcnt(7) lgkmcnt(0)
; DEV f32x4 mfma16(bf16x8 a, bf16x8 b, f32x4 c) { return __builtin_amdgcn_mfma_f32_16x16x32_bf16(a, b, c, 0, 0, 0); }
; DEV void gemm_tile(const u16* __restrict__ A, size_t lda, const u16* __restrict__ Bt, size_t ldb, int K,
;                    u16* sA, u16* sB, f32x4 (&acc)[8][4]) {
;     ...
;           for (int ni = 0; ni < 4; ++ni) acc[mh * 4 + mi][ni] = mfma16(a[mi], b[ni], acc[mh * 4 + mi][ni]);
; DEV void store_tile_f32_add(const f32x4 (&acc)[8][4], const float* xres, float* out, int m0, int n0, unsigned char* smem) {
;     ...
;   float* st = (float*)(smem + wid * 8704);
;   const int chunk = lane & 15;
; #pragma unroll
;   for (int mq = 0; mq < 4; ++mq) {
; #pragma unroll
;     for (int mh = 0; mh < 2; ++mh)
; #pragma unroll
;       for (int ni = 0; ni < 4; ++ni)
; #pragma unroll
;         for (int j = 0; j < 4; ++j) st[(mh * 16 + fq * 4 + j) * 68 + ni * 16 + fr] = acc[mq * 2 + mh][ni][j];
; #pragma unroll
;     for (int itr = 0; itr < 8; ++itr) {
;       const int rl = (lane >> 4) + 4 * itr;
;       const f32x4 v = *(const f32x4*)(st + rl * 68 + chunk * 4);
;       const size_t idx = (size_t)(m0 + wr * 128 + mq * 32 + rl) * 2048 + n0 + wc * 64 + chunk * 4;
;       const f32x4 x = *(const f32x4*)(xres + idx);
;       *(f32x4*)(out + idx) = x + v;
;     }
;   }
	v_mov_b64_e32 v[114:115], v[216:217]
	v_mov_b64_e32 v[116:117], v[218:219]
	v_pk_add_f32 v[112:113], v[112:113], v[116:117]
	v_pk_add_f32 v[110:111], v[110:111], v[114:115]
	v_lshl_add_u64 v[114:115], s[6:7], 0, v[118:119]
	global_store_dwordx4 v[114:115], v[110:113], off
	v_or_b32_e32 v114, v99, v103
	v_ashrrev_i32_e32 v115, 31, v114
	v_lshlrev_b64 v[114:115], 11, v[114:115]
	v_lshl_add_u64 v[114:115], v[114:115], 0, v[100:101]
	v_lshlrev_b64 v[118:119], 2, v[114:115]
	v_lshl_add_u64 v[114:115], s[20:21], 0, v[118:119]
	ds_read_b128 v[110:113], v96 offset:3264
	v_mfma_f32_16x16x32_bf16 v[28:31], v[144:147], v[124:127], v[28:31]
	s_waitcnt vmcnt(7) lgkmcnt(0)
	v_mov_b64_e32 v[114:115], v[220:221]
	v_mov_b64_e32 v[116:117], v[222:223]
	v_pk_add_f32 v[112:113], v[112:113], v[116:117]
	v_pk_add_f32 v[110:111], v[110:111], v[114:115]
	v_lshl_add_u64 v[114:115], s[6:7], 0, v[118:119]
	global_store_dwordx4 v[114:115], v[110:113], off
	v_or_b32_e32 v114, v105, v103
	v_ashrrev_i32_e32 v115, 31, v114
	v_lshlrev_b64 v[114:115], 11, v[114:115]
	v_lshl_add_u64 v[114:115], v[114:115], 0, v[100:101]
	v_lshlrev_b64 v[118:119], 2, v[114:115]
	v_lshl_add_u64 v[114:115], s[20:21], 0, v[118:119]
	ds_read_b128 v[110:113], v96 offset:4352
	v_mfma_f32_16x16x32_bf16 v[0:3], v[152:155], v[136:139], v[0:3]
	s_waitcnt vmcnt(7) lgkmcnt(0)
	v_mov_b64_e32 v[114:115], v[224:225]
	v_mov_b64_e32 v[116:117], v[226:227]
	v_pk_add_f32 v[112:113], v[112:113], v[116:117]
	v_pk_add_f32 v[110:111], v[110:111], v[114:115]
	v_lshl_add_u64 v[114:115], s[6:7], 0, v[118:119]
	global_store_dwordx4 v[114:115], v[110:113], off
	v_or_b32_e32 v114, v107, v103
	v_ashrrev_i32_e32 v115, 31, v114
	v_lshlrev_b64 v[114:115], 11, v[114:115]
	v_lshl_add_u64 v[114:115], v[114:115], 0, v[100:101]
	v_lshlrev_b64 v[118:119], 2, v[114:115]
	v_lshl_add_u64 v[114:115], s[20:21], 0, v[118:119]
	ds_read_b128 v[110:113], v96 offset:5440
	v_mfma_f32_16x16x32_bf16 v[24:27], v[144:147], v[128:131], v[24:27]
	s_waitcnt vmcnt(7) lgkmcnt(0)
	v_mov_b64_e32 v[114:115], v[232:233]
	v_mov_b64_e32 v[116:117], v[234:235]
	v_pk_add_f32 v[112:113], v[112:113], v[116:117]
	v_pk_add_f32 v[110:111], v[110:111], v[114:115]
	v_lshl_add_u64 v[114:115], s[6:7], 0, v[118:119]
	global_store_dwordx4 v[114:115], v[110:113], off
	v_or_b32_e32 v114, v108, v103
	v_ashrrev_i32_e32 v115, 31, v114
	v_lshlrev_b64 v[114:115], 11, v[114:115]
	v_lshl_add_u64 v[114:115], v[114:115], 0, v[100:101]
	v_lshlrev_b64 v[118:119], 2, v[114:115]
	v_lshl_add_u64 v[114:115], s[20:21], 0, v[118:119]
	ds_read_b128 v[110:113], v96 offset:6528
	v_mfma_f32_16x16x32_bf16 v[20:23], v[144:147], v[132:135], v[20:23]
	s_waitcnt vmcnt(7) lgkmcnt(0)
	v_mov_b64_e32 v[114:115], v[236:237]
	v_mov_b64_e32 v[116:117], v[238:239]
	v_pk_add_f32 v[112:113], v[112:113], v[116:117]
	v_pk_add_f32 v[110:111], v[110:111], v[114:115]
	v_lshl_add_u64 v[114:115], s[6:7], 0, v[118:119]
	global_store_dwordx4 v[114:115], v[110:113], off
	ds_write_b32 v106, v92
	ds_write_b32 v106, v93 offset:272
	ds_write_b32 v106, v94 offset:544
	ds_write_b32 v106, v95 offset:816
	ds_write_b32 v106, v88 offset:64
	ds_write_b32 v106, v89 offset:336
	ds_write_b32 v106, v90 offset:608
	ds_write_b32 v106, v91 offset:880
	ds_write_b32 v106, v84 offset:128
	ds_write_b32 v106, v85 offset:400
	ds_write_b32 v106, v86 offset:672
	ds_write_b32 v106, v87 offset:944
	ds_write_b32 v106, v80 offset:192
	ds_write_b32 v106, v81 offset:464
	ds_write_b32 v106, v82 offset:736
	ds_write_b32 v106, v83 offset:1008
	ds_write_b32 v106, v76 offset:4352
	ds_write_b32 v106, v77 offset:4624
	ds_write_b32 v106, v78 offset:4896
	ds_write_b32 v106, v79 offset:5168
	ds_write_b32 v106, v72 offset:4416
	ds_write_b32 v106, v73 offset:4688
	ds_write_b32 v106, v74 offset:4960
	ds_write_b32 v106, v75 offset:5232
	ds_write_b32 v106, v68 offset:4480
	ds_write_b32 v106, v69 offset:4752
	ds_write_b32 v106, v70 offset:5024
	ds_write_b32 v106, v71 offset:5296
	ds_write_b32 v106, v64 offset:4544
	ds_write_b32 v106, v65 offset:4816
	ds_write_b32 v106, v66 offset:5088
	ds_write_b32 v106, v67 offset:5360
	v_or_b32_e32 v64, 32, v103
	v_or_b32_e32 v70, v64, v102
	v_ashrrev_i32_e32 v71, 31, v70
	v_lshlrev_b64 v[70:71], 11, v[70:71]
	v_lshl_add_u64 v[70:71], v[70:71], 0, v[100:101]
	v_lshlrev_b64 v[74:75], 2, v[70:71]
	v_lshl_add_u64 v[70:71], s[20:21], 0, v[74:75]
	v_mov_b32_e32 v242, 0x8000
	v_mov_b32_e32 v243, 0
	v_mov_b64_e32 v[240:241], v[70:71]
	global_load_dwordx4 v[70:73], v[70:71], off
	v_lshl_add_u64 v[240:241], v[240:241], 0, v[242:243]
	global_load_dwordx4 v[208:211], v[240:241], off
	v_lshl_add_u64 v[240:241], v[240:241], 0, v[242:243]
	global_load_dwordx4 v[212:215], v[240:241], off
	v_lshl_add_u64 v[240:241], v[240:241], 0, v[242:243]
	global_load_dwordx4 v[216:219], v[240:241], off
	v_lshl_add_u64 v[240:241], v[240:241], 0, v[242:243]
	global_load_dwordx4 v[220:223], v[240:241], off
	v_lshl_add_u64 v[240:241], v[240:241], 0, v[242:243]
	global_load_dwordx4 v[224:227], v[240:241], off
	v_lshl_add_u64 v[240:241], v[240:241], 0, v[242:243]
	global_load_dwordx4 v[232:235], v[240:241], off
	v_lshl_add_u64 v[240:241], v[240:241], 0, v[242:243]
	global_load_dwordx4 v[236:239], v[240:241], off
	ds_read_b128 v[66:69], v104
	v_mfma_f32_16x16x32_bf16 v[16:19], v[144:147], v[136:139], v[16:19]
	s_waitcnt vmcnt(7) lgkmcnt(0)
	v_pk_add_f32 v[68:69], v[68:69], v[72:73]
	v_pk_add_f32 v[66:67], v[66:67], v[70:71]
	v_lshl_add_u64 v[70:71], s[6:7], 0, v[74:75]
	global_store_dwordx4 v[70:71], v[66:69], off
	v_or_b32_e32 v70, v64, v109
	v_ashrrev_i32_e32 v71, 31, v70
	v_lshlrev_b64 v[70:71], 11, v[70:71]
	v_lshl_add_u64 v[70:71], v[70:71], 0, v[100:101]
	v_lshlrev_b64 v[74:75], 2, v[70:71]
	v_lshl_add_u64 v[70:71], s[20:21], 0, v[74:75]
	ds_read_b128 v[66:69], v96
	v_mfma_f32_16x16x32_bf16 v[12:15], v[152:155], v[124:127], v[12:15]
	s_waitcnt vmcnt(7) lgkmcnt(0)
; DEV void store_tile_f32_add(const f32x4 (&acc)[8][4], const float* xres, float* out, int m0, int n0, unsigned char* smem) {
;     ...
;   float* st = (float*)(smem + wid * 8704);
;   const int chunk = lane & 15;
; #pragma unroll
;   for (int mq = 0; mq < 4; ++mq) {
; #pragma unroll
;     for (int mh = 0; mh < 2; ++mh)
; #pragma unroll
;       for (int ni = 0; ni < 4; ++ni)
; #pragma unroll
;         for (int j = 0; j < 4; ++j) st[(mh * 16 + fq * 4 + j) * 68 + ni * 16 + fr] = acc[mq * 2 + mh][ni][j];
; #pragma unroll
;     for (int itr = 0; itr < 8; ++itr) {
;       const int rl = (lane >> 4) + 4 * itr;
;       const f32x4 v = *(const f32x4*)(st + rl * 68 + chunk * 4);
;       const size_t idx = (size_t)(m0 + wr * 128 + mq * 32 + rl) * 2048 + n0 + wc * 64 + chunk * 4;
;       const f32x4 x = *(const f32x4*)(xres + idx);
;       *(f32x4*)(out + idx) = x + v;
;     }
;   }
	v_mov_b64_e32 v[70:71], v[208:209]
	v_mov_b64_e32 v[72:73], v[210:211]
	v_pk_add_f32 v[68:69], v[68:69], v[72:73]
	v_pk_add_f32 v[66:67], v[66:67], v[70:71]
	v_lshl_add_u64 v[70:71], s[6:7], 0, v[74:75]
	global_store_dwordx4 v[70:71], v[66:69], off
	v_or_b32_e32 v70, v64, v97
	v_ashrrev_i32_e32 v71, 31, v70
	v_lshlrev_b64 v[70:71], 11, v[70:71]
	v_lshl_add_u64 v[70:71], v[70:71], 0, v[100:101]
	v_lshlrev_b64 v[74:75], 2, v[70:71]
	v_lshl_add_u64 v[70:71], s[20:21], 0, v[74:75]
	ds_read_b128 v[66:69], v96 offset:1088
	v_mfma_f32_16x16x32_bf16 v[8:11], v[152:155], v[128:131], v[8:11]
	s_waitcnt vmcnt(7) lgkmcnt(0)
	v_mov_b64_e32 v[70:71], v[212:213]
	v_mov_b64_e32 v[72:73], v[214:215]
	v_pk_add_f32 v[68:69], v[68:69], v[72:73]
	v_pk_add_f32 v[66:67], v[66:67], v[70:71]
	v_lshl_add_u64 v[70:71], s[6:7], 0, v[74:75]
	global_store_dwordx4 v[70:71], v[66:69], off
	v_or_b32_e32 v70, v64, v98
	v_ashrrev_i32_e32 v71, 31, v70
	v_lshlrev_b64 v[70:71], 11, v[70:71]
	v_lshl_add_u64 v[70:71], v[70:71], 0, v[100:101]
	v_lshlrev_b64 v[74:75], 2, v[70:71]
	v_lshl_add_u64 v[70:71], s[20:21], 0, v[74:75]
	ds_read_b128 v[66:69], v96 offset:2176
	v_mfma_f32_16x16x32_bf16 v[4:7], v[152:155], v[132:135], v[4:7]
	s_waitcnt vmcnt(7) lgkmcnt(0)
	v_mov_b64_e32 v[70:71], v[216:217]
	v_mov_b64_e32 v[72:73], v[218:219]
	v_pk_add_f32 v[68:69], v[68:69], v[72:73]
	v_pk_add_f32 v[66:67], v[66:67], v[70:71]
	v_lshl_add_u64 v[70:71], s[6:7], 0, v[74:75]
	global_store_dwordx4 v[70:71], v[66:69], off
	v_or_b32_e32 v70, v64, v99
	v_ashrrev_i32_e32 v71, 31, v70
	v_lshlrev_b64 v[70:71], 11, v[70:71]
	v_lshl_add_u64 v[70:71], v[70:71], 0, v[100:101]
	v_lshlrev_b64 v[74:75], 2, v[70:71]
	v_lshl_add_u64 v[70:71], s[20:21], 0, v[74:75]
	ds_read_b128 v[66:69], v96 offset:3264
	s_waitcnt vmcnt(7) lgkmcnt(0)
	v_mov_b64_e32 v[70:71], v[220:221]
	v_mov_b64_e32 v[72:73], v[222:223]
	v_pk_add_f32 v[68:69], v[68:69], v[72:73]
	v_pk_add_f32 v[66:67], v[66:67], v[70:71]
	v_lshl_add_u64 v[70:71], s[6:7], 0, v[74:75]
	global_store_dwordx4 v[70:71], v[66:69], off
	v_or_b32_e32 v70, v64, v105
	v_ashrrev_i32_e32 v71, 31, v70
	v_lshlrev_b64 v[70:71], 11, v[70:71]
	v_lshl_add_u64 v[70:71], v[70:71], 0, v[100:101]
	v_lshlrev_b64 v[74:75], 2, v[70:71]
	v_lshl_add_u64 v[70:71], s[20:21], 0, v[74:75]
	ds_read_b128 v[66:69], v96 offset:4352
	s_waitcnt vmcnt(7) lgkmcnt(0)
	v_mov_b64_e32 v[70:71], v[224:225]
	v_mov_b64_e32 v[72:73], v[226:227]
	v_pk_add_f32 v[68:69], v[68:69], v[72:73]
	v_pk_add_f32 v[66:67], v[66:67], v[70:71]
	v_lshl_add_u64 v[70:71], s[6:7], 0, v[74:75]
	global_store_dwordx4 v[70:71], v[66:69], off
	v_or_b32_e32 v70, v64, v107
	v_ashrrev_i32_e32 v71, 31, v70
	v_lshlrev_b64 v[70:71], 11, v[70:71]
	v_lshl_add_u64 v[70:71], v[70:71], 0, v[100:101]
	v_lshlrev_b64 v[74:75], 2, v[70:71]
	v_lshl_add_u64 v[70:71], s[20:21], 0, v[74:75]
	ds_read_b128 v[66:69], v96 offset:5440
	v_or_b32_e32 v64, v64, v108
	v_ashrrev_i32_e32 v65, 31, v64
	v_lshlrev_b64 v[64:65], 11, v[64:65]
	v_lshl_add_u64 v[64:65], v[64:65], 0, v[100:101]
	v_lshlrev_b64 v[64:65], 2, v[64:65]
	s_waitcnt vmcnt(7) lgkmcnt(0)
	v_mov_b64_e32 v[70:71], v[232:233]
	v_mov_b64_e32 v[72:73], v[234:235]
	v_pk_add_f32 v[68:69], v[68:69], v[72:73]
	v_pk_add_f32 v[66:67], v[66:67], v[70:71]
	v_lshl_add_u64 v[70:71], s[6:7], 0, v[74:75]
	global_store_dwordx4 v[70:71], v[66:69], off
	v_lshl_add_u64 v[70:71], s[20:21], 0, v[64:65]
	ds_read_b128 v[66:69], v96 offset:6528
	v_lshl_add_u64 v[64:65], s[6:7], 0, v[64:65]
	s_waitcnt vmcnt(7) lgkmcnt(0)
	v_mov_b64_e32 v[70:71], v[236:237]
	v_mov_b64_e32 v[72:73], v[238:239]
	v_pk_add_f32 v[68:69], v[68:69], v[72:73]
	v_pk_add_f32 v[66:67], v[66:67], v[70:71]
	global_store_dwordx4 v[64:65], v[66:69], off
	ds_write_b32 v106, v60
	ds_write_b32 v106, v61 offset:272
	ds_write_b32 v106, v62 offset:544
	ds_write_b32 v106, v63 offset:816
	ds_write_b32 v106, v56 offset:64
	ds_write_b32 v106, v57 offset:336
	ds_write_b32 v106, v58 offset:608
	ds_write_b32 v106, v59 offset:880
	ds_write_b32 v106, v52 offset:128
	ds_write_b32 v106, v53 offset:400
	ds_write_b32 v106, v54 offset:672
	ds_write_b32 v106, v55 offset:944
	ds_write_b32 v106, v48 offset:192
	ds_write_b32 v106, v49 offset:464
	ds_write_b32 v106, v50 offset:736
	ds_write_b32 v106, v51 offset:1008
	ds_write_b32 v106, v44 offset:4352
	ds_write_b32 v106, v45 offset:4624
	ds_write_b32 v106, v46 offset:4896
	ds_write_b32 v106, v47 offset:5168
	ds_write_b32 v106, v40 offset:4416
	ds_write_b32 v106, v41 offset:4688
	ds_write_b32 v106, v42 offset:4960
	ds_write_b32 v106, v43 offset:5232
	ds_write_b32 v106, v36 offset:4480
	ds_write_b32 v106, v37 offset:4752
	ds_write_b32 v106, v38 offset:5024
	ds_write_b32 v106, v39 offset:5296
	ds_write_b32 v106, v32 offset:4544
	ds_write_b32 v106, v33 offset:4816
	ds_write_b32 v106, v34 offset:5088
	ds_write_b32 v106, v35 offset:5360
	v_or_b32_e32 v32, 64, v103
	v_or_b32_e32 v38, v32, v102
	v_ashrrev_i32_e32 v39, 31, v38
	v_lshlrev_b64 v[38:39], 11, v[38:39]
	v_lshl_add_u64 v[38:39], v[38:39], 0, v[100:101]
	v_lshlrev_b64 v[42:43], 2, v[38:39]
	v_lshl_add_u64 v[38:39], s[20:21], 0, v[42:43]
	v_mov_b32_e32 v242, 0x8000
	v_mov_b32_e32 v243, 0
	v_mov_b64_e32 v[240:241], v[38:39]
	global_load_dwordx4 v[38:41], v[38:39], off
	v_lshl_add_u64 v[240:241], v[240:241], 0, v[242:243]
	global_load_dwordx4 v[208:211], v[240:241], off
	v_lshl_add_u64 v[240:241], v[240:241], 0, v[242:243]
	global_load_dwordx4 v[212:215], v[240:241], off
	v_lshl_add_u64 v[240:241], v[240:241], 0, v[242:243]
	global_load_dwordx4 v[216:219], v[240:241], off
	v_lshl_add_u64 v[240:241], v[240:241], 0, v[242:243]
	global_load_dwordx4 v[220:223], v[240:241], off
	v_lshl_add_u64 v[240:241], v[240:241], 0, v[242:243]
	global_load_dwordx4 v[224:227], v[240:241], off
	v_lshl_add_u64 v[240:241], v[240:241], 0, v[242:243]
	global_load_dwordx4 v[232:235], v[240:241], off
	v_lshl_add_u64 v[240:241], v[240:241], 0, v[242:243]
	global_load_dwordx4 v[236:239], v[240:241], off
	ds_read_b128 v[34:37], v104
	s_waitcnt vmcnt(7) lgkmcnt(0)
; DEV void store_tile_f32_add(const f32x4 (&acc)[8][4], const float* xres, float* out, int m0, int n0, unsigned char* smem) {
;     ...
;   float* st = (float*)(smem + wid * 8704);
;   const int chunk = lane & 15;
; #pragma unroll
;   for (int mq = 0; mq < 4; ++mq) {
; #pragma unroll
;     for (int mh = 0; mh < 2; ++mh)
; #pragma unroll
;       for (int ni = 0; ni < 4; ++ni)
; #pragma unroll
;         for (int j = 0; j < 4; ++j) st[(mh * 16 + fq * 4 + j) * 68 + ni * 16 + fr] = acc[mq * 2 + mh][ni][j];
; #pragma unroll
;     for (int itr = 0; itr < 8; ++itr) {
;       const int rl = (lane >> 4) + 4 * itr;
;       const f32x4 v = *(const f32x4*)(st + rl * 68 + chunk * 4);
;       const size_t idx = (size_t)(m0 + wr * 128 + mq * 32 + rl) * 2048 + n0 + wc * 64 + chunk * 4;
;       const f32x4 x = *(const f32x4*)(xres + idx);
;       *(f32x4*)(out + idx) = x + v;
;     }
;   }
	v_pk_add_f32 v[36:37], v[36:37], v[40:41]
	v_pk_add_f32 v[34:35], v[34:35], v[38:39]
	v_lshl_add_u64 v[38:39], s[6:7], 0, v[42:43]
	global_store_dwordx4 v[38:39], v[34:37], off
	v_or_b32_e32 v38, v32, v109
	v_ashrrev_i32_e32 v39, 31, v38
	v_lshlrev_b64 v[38:39], 11, v[38:39]
	v_lshl_add_u64 v[38:39], v[38:39], 0, v[100:101]
	v_lshlrev_b64 v[42:43], 2, v[38:39]
	v_lshl_add_u64 v[38:39], s[20:21], 0, v[42:43]
	ds_read_b128 v[34:37], v96
	s_waitcnt vmcnt(7) lgkmcnt(0)
	v_mov_b64_e32 v[38:39], v[208:209]
	v_mov_b64_e32 v[40:41], v[210:211]
	v_pk_add_f32 v[36:37], v[36:37], v[40:41]
	v_pk_add_f32 v[34:35], v[34:35], v[38:39]
	v_lshl_add_u64 v[38:39], s[6:7], 0, v[42:43]
	global_store_dwordx4 v[38:39], v[34:37], off
	v_or_b32_e32 v38, v32, v97
	v_ashrrev_i32_e32 v39, 31, v38
	v_lshlrev_b64 v[38:39], 11, v[38:39]
	v_lshl_add_u64 v[38:39], v[38:39], 0, v[100:101]
	v_lshlrev_b64 v[42:43], 2, v[38:39]
	v_lshl_add_u64 v[38:39], s[20:21], 0, v[42:43]
	ds_read_b128 v[34:37], v96 offset:1088
	s_waitcnt vmcnt(7) lgkmcnt(0)
	v_mov_b64_e32 v[38:39], v[212:213]
	v_mov_b64_e32 v[40:41], v[214:215]
	v_pk_add_f32 v[36:37], v[36:37], v[40:41]
	v_pk_add_f32 v[34:35], v[34:35], v[38:39]
	v_lshl_add_u64 v[38:39], s[6:7], 0, v[42:43]
	global_store_dwordx4 v[38:39], v[34:37], off
	v_or_b32_e32 v38, v32, v98
	v_ashrrev_i32_e32 v39, 31, v38
	v_lshlrev_b64 v[38:39], 11, v[38:39]
	v_lshl_add_u64 v[38:39], v[38:39], 0, v[100:101]
	v_lshlrev_b64 v[42:43], 2, v[38:39]
	v_lshl_add_u64 v[38:39], s[20:21], 0, v[42:43]
	ds_read_b128 v[34:37], v96 offset:2176
	s_waitcnt vmcnt(7) lgkmcnt(0)
	v_mov_b64_e32 v[38:39], v[216:217]
	v_mov_b64_e32 v[40:41], v[218:219]
	v_pk_add_f32 v[36:37], v[36:37], v[40:41]
	v_pk_add_f32 v[34:35], v[34:35], v[38:39]
	v_lshl_add_u64 v[38:39], s[6:7], 0, v[42:43]
	global_store_dwordx4 v[38:39], v[34:37], off
	v_or_b32_e32 v38, v32, v99
	v_ashrrev_i32_e32 v39, 31, v38
	v_lshlrev_b64 v[38:39], 11, v[38:39]
	v_lshl_add_u64 v[38:39], v[38:39], 0, v[100:101]
	v_lshlrev_b64 v[42:43], 2, v[38:39]
	v_lshl_add_u64 v[38:39], s[20:21], 0, v[42:43]
	ds_read_b128 v[34:37], v96 offset:3264
	s_waitcnt vmcnt(7) lgkmcnt(0)
	v_mov_b64_e32 v[38:39], v[220:221]
	v_mov_b64_e32 v[40:41], v[222:223]
	v_pk_add_f32 v[36:37], v[36:37], v[40:41]
	v_pk_add_f32 v[34:35], v[34:35], v[38:39]
	v_lshl_add_u64 v[38:39], s[6:7], 0, v[42:43]
	global_store_dwordx4 v[38:39], v[34:37], off
	v_or_b32_e32 v38, v32, v105
	v_ashrrev_i32_e32 v39, 31, v38
	v_lshlrev_b64 v[38:39], 11, v[38:39]
	v_lshl_add_u64 v[38:39], v[38:39], 0, v[100:101]
	v_lshlrev_b64 v[42:43], 2, v[38:39]
	v_lshl_add_u64 v[38:39], s[20:21], 0, v[42:43]
	ds_read_b128 v[34:37], v96 offset:4352
	s_waitcnt vmcnt(7) lgkmcnt(0)
	v_mov_b64_e32 v[38:39], v[224:225]
	v_mov_b64_e32 v[40:41], v[226:227]
	v_pk_add_f32 v[36:37], v[36:37], v[40:41]
	v_pk_add_f32 v[34:35], v[34:35], v[38:39]
	v_lshl_add_u64 v[38:39], s[6:7], 0, v[42:43]
	global_store_dwordx4 v[38:39], v[34:37], off
	v_or_b32_e32 v38, v32, v107
	v_ashrrev_i32_e32 v39, 31, v38
	v_lshlrev_b64 v[38:39], 11, v[38:39]
	v_lshl_add_u64 v[38:39], v[38:39], 0, v[100:101]
	v_lshlrev_b64 v[42:43], 2, v[38:39]
	v_lshl_add_u64 v[38:39], s[20:21], 0, v[42:43]
	ds_read_b128 v[34:37], v96 offset:5440
	v_or_b32_e32 v32, v32, v108
	v_ashrrev_i32_e32 v33, 31, v32
	v_lshlrev_b64 v[32:33], 11, v[32:33]
	v_lshl_add_u64 v[32:33], v[32:33], 0, v[100:101]
	v_lshlrev_b64 v[32:33], 2, v[32:33]
	s_waitcnt vmcnt(7) lgkmcnt(0)
	v_mov_b64_e32 v[38:39], v[232:233]
	v_mov_b64_e32 v[40:41], v[234:235]
	v_pk_add_f32 v[36:37], v[36:37], v[40:41]
	v_pk_add_f32 v[34:35], v[34:35], v[38:39]
	v_lshl_add_u64 v[38:39], s[6:7], 0, v[42:43]
	global_store_dwordx4 v[38:39], v[34:37], off
	v_lshl_add_u64 v[38:39], s[20:21], 0, v[32:33]
	ds_read_b128 v[34:37], v96 offset:6528
	v_lshl_add_u64 v[32:33], s[6:7], 0, v[32:33]
	s_waitcnt vmcnt(7) lgkmcnt(0)
; DEV void store_tile_f32_add(const f32x4 (&acc)[8][4], const float* xres, float* out, int m0, int n0, unsigned char* smem) {
;     ...
;   float* st = (float*)(smem + wid * 8704);
;   const int chunk = lane & 15;
; #pragma unroll
;   for (int mq = 0; mq < 4; ++mq) {
; #pragma unroll
;     for (int mh = 0; mh < 2; ++mh)
; #pragma unroll
;       for (int ni = 0; ni < 4; ++ni)
; #pragma unroll
;         for (int j = 0; j < 4; ++j) st[(mh * 16 + fq * 4 + j) * 68 + ni * 16 + fr] = acc[mq * 2 + mh][ni][j];
; #pragma unroll
;     for (int itr = 0; itr < 8; ++itr) {
;       const int rl = (lane >> 4) + 4 * itr;
;       const f32x4 v = *(const f32x4*)(st + rl * 68 + chunk * 4);
;       const size_t idx = (size_t)(m0 + wr * 128 + mq * 32 + rl) * 2048 + n0 + wc * 64 + chunk * 4;
;       const f32x4 x = *(const f32x4*)(xres + idx);
;       *(f32x4*)(out + idx) = x + v;
;     }
;   }
	v_mov_b64_e32 v[38:39], v[236:237]
	v_mov_b64_e32 v[40:41], v[238:239]
	v_pk_add_f32 v[36:37], v[36:37], v[40:41]
	v_pk_add_f32 v[34:35], v[34:35], v[38:39]
	global_store_dwordx4 v[32:33], v[34:37], off
	ds_write_b32 v106, v28
	ds_write_b32 v106, v29 offset:272
	ds_write_b32 v106, v30 offset:544
	ds_write_b32 v106, v31 offset:816
	ds_write_b32 v106, v24 offset:64
	ds_write_b32 v106, v25 offset:336
	ds_write_b32 v106, v26 offset:608
	ds_write_b32 v106, v27 offset:880
	ds_write_b32 v106, v20 offset:128
	ds_write_b32 v106, v21 offset:400
	ds_write_b32 v106, v22 offset:672
	ds_write_b32 v106, v23 offset:944
	ds_write_b32 v106, v16 offset:192
	ds_write_b32 v106, v17 offset:464
	ds_write_b32 v106, v18 offset:736
	ds_write_b32 v106, v19 offset:1008
	ds_write_b32 v106, v12 offset:4352
	ds_write_b32 v106, v13 offset:4624
	ds_write_b32 v106, v14 offset:4896
	ds_write_b32 v106, v15 offset:5168
	ds_write_b32 v106, v8 offset:4416
	ds_write_b32 v106, v9 offset:4688
	ds_write_b32 v106, v10 offset:4960
	ds_write_b32 v106, v11 offset:5232
	ds_write_b32 v106, v4 offset:4480
	ds_write_b32 v106, v5 offset:4752
	ds_write_b32 v106, v6 offset:5024
	ds_write_b32 v106, v7 offset:5296
	ds_write_b32 v106, v0 offset:4544
	ds_write_b32 v106, v1 offset:4816
	ds_write_b32 v106, v2 offset:5088
	ds_write_b32 v106, v3 offset:5360
	v_or_b32_e32 v0, 0x60, v103
	v_or_b32_e32 v6, v0, v102
	v_ashrrev_i32_e32 v7, 31, v6
	v_lshlrev_b64 v[6:7], 11, v[6:7]
	v_lshl_add_u64 v[6:7], v[6:7], 0, v[100:101]
	v_lshlrev_b64 v[10:11], 2, v[6:7]
	v_lshl_add_u64 v[6:7], s[20:21], 0, v[10:11]
	v_mov_b32_e32 v242, 0x8000
	v_mov_b32_e32 v243, 0
	v_mov_b64_e32 v[240:241], v[6:7]
	global_load_dwordx4 v[6:9], v[6:7], off
	v_lshl_add_u64 v[240:241], v[240:241], 0, v[242:243]
	global_load_dwordx4 v[208:211], v[240:241], off
	v_lshl_add_u64 v[240:241], v[240:241], 0, v[242:243]
	global_load_dwordx4 v[212:215], v[240:241], off
	v_lshl_add_u64 v[240:241], v[240:241], 0, v[242:243]
	global_load_dwordx4 v[216:219], v[240:241], off
	v_lshl_add_u64 v[240:241], v[240:241], 0, v[242:243]
	global_load_dwordx4 v[220:223], v[240:241], off
	v_lshl_add_u64 v[240:241], v[240:241], 0, v[242:243]
	global_load_dwordx4 v[224:227], v[240:241], off
	v_lshl_add_u64 v[240:241], v[240:241], 0, v[242:243]
	global_load_dwordx4 v[232:235], v[240:241], off
	v_lshl_add_u64 v[240:241], v[240:241], 0, v[242:243]
	global_load_dwordx4 v[236:239], v[240:241], off
	ds_read_b128 v[2:5], v104
	s_waitcnt vmcnt(7) lgkmcnt(0)
	v_pk_add_f32 v[4:5], v[4:5], v[8:9]
	v_pk_add_f32 v[2:3], v[2:3], v[6:7]
	v_lshl_add_u64 v[6:7], s[6:7], 0, v[10:11]
	global_store_dwordx4 v[6:7], v[2:5], off
	v_or_b32_e32 v6, v0, v109
	v_ashrrev_i32_e32 v7, 31, v6
	v_lshlrev_b64 v[6:7], 11, v[6:7]
	v_lshl_add_u64 v[6:7], v[6:7], 0, v[100:101]
	v_lshlrev_b64 v[10:11], 2, v[6:7]
	v_lshl_add_u64 v[6:7], s[20:21], 0, v[10:11]
	ds_read_b128 v[2:5], v96
	s_waitcnt vmcnt(7) lgkmcnt(0)
	v_mov_b64_e32 v[6:7], v[208:209]
	v_mov_b64_e32 v[8:9], v[210:211]
	v_pk_add_f32 v[4:5], v[4:5], v[8:9]
	v_pk_add_f32 v[2:3], v[2:3], v[6:7]
	v_lshl_add_u64 v[6:7], s[6:7], 0, v[10:11]
	global_store_dwordx4 v[6:7], v[2:5], off
	v_or_b32_e32 v6, v0, v97
	v_ashrrev_i32_e32 v7, 31, v6
	v_lshlrev_b64 v[6:7], 11, v[6:7]
	v_lshl_add_u64 v[6:7], v[6:7], 0, v[100:101]
	v_lshlrev_b64 v[10:11], 2, v[6:7]
	v_lshl_add_u64 v[6:7], s[20:21], 0, v[10:11]
	ds_read_b128 v[2:5], v96 offset:1088
	s_waitcnt vmcnt(7) lgkmcnt(0)
	v_mov_b64_e32 v[6:7], v[212:213]
	v_mov_b64_e32 v[8:9], v[214:215]
	v_pk_add_f32 v[4:5], v[4:5], v[8:9]
	v_pk_add_f32 v[2:3], v[2:3], v[6:7]
	v_lshl_add_u64 v[6:7], s[6:7], 0, v[10:11]
	global_store_dwordx4 v[6:7], v[2:5], off
	v_or_b32_e32 v6, v0, v98
	v_ashrrev_i32_e32 v7, 31, v6
	v_lshlrev_b64 v[6:7], 11, v[6:7]
	v_lshl_add_u64 v[6:7], v[6:7], 0, v[100:101]
	v_lshlrev_b64 v[10:11], 2, v[6:7]
	v_lshl_add_u64 v[6:7], s[20:21], 0, v[10:11]
	ds_read_b128 v[2:5], v96 offset:2176
	s_waitcnt vmcnt(7) lgkmcnt(0)
	v_mov_b64_e32 v[6:7], v[216:217]
	v_mov_b64_e32 v[8:9], v[218:219]
	v_pk_add_f32 v[4:5], v[4:5], v[8:9]
	v_pk_add_f32 v[2:3], v[2:3], v[6:7]
	v_lshl_add_u64 v[6:7], s[6:7], 0, v[10:11]
	global_store_dwordx4 v[6:7], v[2:5], off
	v_or_b32_e32 v6, v0, v99
	v_ashrrev_i32_e32 v7, 31, v6
	v_lshlrev_b64 v[6:7], 11, v[6:7]
	v_lshl_add_u64 v[6:7], v[6:7], 0, v[100:101]
	v_lshlrev_b64 v[10:11], 2, v[6:7]
	v_lshl_add_u64 v[6:7], s[20:21], 0, v[10:11]
	ds_read_b128 v[2:5], v96 offset:3264
	s_waitcnt vmcnt(7) lgkmcnt(0)
	v_mov_b64_e32 v[6:7], v[220:221]
	v_mov_b64_e32 v[8:9], v[222:223]
	v_pk_add_f32 v[4:5], v[4:5], v[8:9]
	v_pk_add_f32 v[2:3], v[2:3], v[6:7]
	v_lshl_add_u64 v[6:7], s[6:7], 0, v[10:11]
	global_store_dwordx4 v[6:7], v[2:5], off
	v_or_b32_e32 v6, v0, v105
	v_ashrrev_i32_e32 v7, 31, v6
	v_lshlrev_b64 v[6:7], 11, v[6:7]
	v_lshl_add_u64 v[6:7], v[6:7], 0, v[100:101]
	v_lshlrev_b64 v[10:11], 2, v[6:7]
	v_lshl_add_u64 v[6:7], s[20:21], 0, v[10:11]
	ds_read_b128 v[2:5], v96 offset:4352
	s_waitcnt vmcnt(7) lgkmcnt(0)
	v_mov_b64_e32 v[6:7], v[224:225]
	v_mov_b64_e32 v[8:9], v[226:227]
	v_pk_add_f32 v[4:5], v[4:5], v[8:9]
	v_pk_add_f32 v[2:3], v[2:3], v[6:7]
	v_lshl_add_u64 v[6:7], s[6:7], 0, v[10:11]
	global_store_dwordx4 v[6:7], v[2:5], off
	v_or_b32_e32 v6, v0, v107
	v_ashrrev_i32_e32 v7, 31, v6
	v_lshlrev_b64 v[6:7], 11, v[6:7]
	v_lshl_add_u64 v[6:7], v[6:7], 0, v[100:101]
	v_lshlrev_b64 v[10:11], 2, v[6:7]
	v_lshl_add_u64 v[6:7], s[20:21], 0, v[10:11]
	ds_read_b128 v[2:5], v96 offset:5440
	v_or_b32_e32 v0, v0, v108
	v_ashrrev_i32_e32 v1, 31, v0
	v_lshlrev_b64 v[0:1], 11, v[0:1]
	v_lshl_add_u64 v[0:1], v[0:1], 0, v[100:101]
	v_lshlrev_b64 v[0:1], 2, v[0:1]
	s_waitcnt vmcnt(7) lgkmcnt(0)
	v_mov_b64_e32 v[6:7], v[232:233]
	v_mov_b64_e32 v[8:9], v[234:235]
	v_pk_add_f32 v[4:5], v[4:5], v[8:9]
	v_pk_add_f32 v[2:3], v[2:3], v[6:7]
	v_lshl_add_u64 v[6:7], s[6:7], 0, v[10:11]
	global_store_dwordx4 v[6:7], v[2:5], off
	v_lshl_add_u64 v[6:7], s[20:21], 0, v[0:1]
	ds_read_b128 v[2:5], v96 offset:6528
	v_lshl_add_u64 v[0:1], s[6:7], 0, v[0:1]
	s_waitcnt vmcnt(7) lgkmcnt(0)
	v_mov_b64_e32 v[6:7], v[236:237]
	v_mov_b64_e32 v[8:9], v[238:239]
	v_pk_add_f32 v[4:5], v[4:5], v[8:9]
	v_pk_add_f32 v[2:3], v[2:3], v[6:7]
	global_store_dwordx4 v[0:1], v[2:5], off
	s_branch .LBB0_244
